# sample scan: next item's conv inputs prefetched before the state stores (store drain overlaps next item), invariants stashed in LDS, D via s_load, 4-wide gating
# baseline (speedup 1.0000x reference)
.LBB0_719:
	v_readlane_b32 s0, v254, 27
	v_readlane_b32 s80, v255, 24
	v_readlane_b32 s1, v254, 28
	v_readlane_b32 s84, v254, 1
	s_lshl_b32 s8, s80, 7
	v_mov_b32_e32 v147, v232
	s_andn2_b64 vcc, exec, s[0:1]
	v_readlane_b32 s34, v254, 31
	v_readlane_b32 s35, v254, 32
	v_readlane_b32 s36, v254, 60
	s_mov_b32 s37, 0x18000
	s_mov_b32 s17, 0x8000
	v_readlane_b32 s85, v254, 2
	v_readlane_b32 s81, v255, 25
	s_cbranch_vccnz .LBB0_842
	v_readlane_b32 s0, v254, 37
	s_add_i32 s0, s8, s0
	s_ashr_i32 s1, s0, 31
	v_ashrrev_i32_e32 v142, 3, v147
	s_lshl_b64 s[0:1], s[0:1], 20
	v_readlane_b32 s6, v254, 29
	s_add_u32 s0, s6, s0
	v_readlane_b32 s6, v254, 30
	v_lshlrev_b32_e32 v144, 7, v142
	s_addc_u32 s1, s6, s1
	v_and_b32_e32 v4, 7, v147
	v_ashrrev_i32_e32 v145, 31, v144
	v_lshl_add_u64 v[0:1], v[144:145], 2, s[0:1]
	v_lshlrev_b32_e32 v48, 4, v4
	v_lshl_add_u64 v[0:1], v[0:1], 0, v[48:49]
	v_add_co_u32_e32 v2, vcc, s17, v0
	global_load_dwordx4 v[122:125], v[0:1], off
	global_load_dwordx4 v[106:109], v[0:1], off offset:128
	global_load_dwordx4 v[90:93], v[0:1], off offset:256
	global_load_dwordx4 v[74:77], v[0:1], off offset:384
	v_addc_co_u32_e32 v3, vcc, 0, v1, vcc
	global_load_dwordx4 v[126:129], v[2:3], off
	global_load_dwordx4 v[110:113], v[2:3], off offset:128
	global_load_dwordx4 v[94:97], v[2:3], off offset:256
	global_load_dwordx4 v[78:81], v[2:3], off offset:384
	v_add_co_u32_e32 v2, vcc, s13, v0
	s_movk_i32 s0, 0xff
	s_nop 0
	v_addc_co_u32_e32 v3, vcc, 0, v1, vcc
	v_add_co_u32_e32 v0, vcc, s37, v0
	global_load_dwordx4 v[130:133], v[2:3], off
	global_load_dwordx4 v[114:117], v[2:3], off offset:128
	global_load_dwordx4 v[98:101], v[2:3], off offset:256
	global_load_dwordx4 v[82:85], v[2:3], off offset:384
	v_addc_co_u32_e32 v1, vcc, 0, v1, vcc
	global_load_dwordx4 v[134:137], v[0:1], off
	global_load_dwordx4 v[118:121], v[0:1], off offset:128
	global_load_dwordx4 v[102:105], v[0:1], off offset:256
	global_load_dwordx4 v[86:89], v[0:1], off offset:384
	v_and_b32_e32 v1, 64, v233
	v_cmp_lt_i32_e64 s[0:1], s0, v147
	v_xor_b32_e32 v0, 1, v233
	v_add_u32_e32 v1, 64, v1
	v_writelane_b32 v252, s0, 49
	v_cmp_lt_i32_e32 vcc, v0, v1
	s_add_u32 s82, s42, 0x4000
	v_writelane_b32 v252, s1, 50
	s_movk_i32 s0, 0x17f
	v_cndmask_b32_e32 v0, v233, v0, vcc
	v_cmp_lt_u32_e64 s[0:1], s0, v147
	v_lshlrev_b32_e32 v216, 2, v0
	v_xor_b32_e32 v0, 2, v233
	v_writelane_b32 v255, s0, 16
	v_cmp_lt_i32_e32 vcc, v0, v1
	s_addc_u32 s83, s43, 0
	v_writelane_b32 v255, s1, 17
	v_cmp_gt_i32_e64 s[0:1], 32, v147
	v_cndmask_b32_e32 v0, v233, v0, vcc
	v_lshlrev_b32_e32 v217, 2, v0
	v_writelane_b32 v255, s0, 14
	v_xor_b32_e32 v0, 4, v233
	v_cmp_lt_i32_e32 vcc, v0, v1
	v_writelane_b32 v255, s1, 15
	s_movk_i32 s0, 0x180
	s_add_u32 s86, s42, 0x8000
	v_cndmask_b32_e32 v0, v233, v0, vcc
	v_cmp_gt_u32_e32 vcc, s0, v147
	v_mov_b32_e32 v1, 0x2a00
	v_mov_b32_e32 v2, 0x1c00
	s_addc_u32 s87, s43, 0
	v_lshl_add_u32 v212, v147, 2, 0
	v_cndmask_b32_e32 v1, v1, v2, vcc
	s_movk_i32 s0, 0x100
	s_add_u32 s80, s42, 0xc000
	v_lshl_add_u32 v201, v142, 2, 0
	v_lshlrev_b32_e32 v218, 2, v0
	v_lshlrev_b32_e32 v0, 10, v4
	v_add_u32_e32 v1, v212, v1
	v_cmp_gt_i32_e32 vcc, s0, v147
	s_addc_u32 s81, s43, 0
	v_lshlrev_b32_e32 v146, 2, v4
	v_or_b32_e32 v200, 0x4000, v4
	v_add_u32_e32 v210, 0xa80, v147
	v_add_u32_e32 v211, 0x700, v147
	v_ashrrev_i32_e32 v213, 2, v147
	v_and_b32_e32 v214, 3, v147
	v_ashrrev_i32_e32 v143, 31, v142
	v_add_u32_e32 v215, 0, v48
	v_cndmask_b32_e32 v219, v1, v212, vcc
	v_cmp_eq_u32_e64 s[46:47], 0, v4
	v_cmp_eq_u32_e64 s[48:49], 1, v4
	v_cmp_eq_u32_e64 s[50:51], 2, v4
	v_cmp_eq_u32_e64 s[52:53], 3, v4
	v_cmp_eq_u32_e64 s[54:55], 4, v4
	v_cmp_eq_u32_e64 s[56:57], 5, v4
	v_cmp_eq_u32_e64 s[58:59], 6, v4
	v_cmp_eq_u32_e64 s[60:61], 7, v4
	v_add_u32_e32 v220, v201, v0
	v_readlane_b32 s9, v254, 59
	s_mov_b32 s62, s2
	s_and_b32 s63, s62, 7
	s_lshl_b32 s0, s63, 7
	v_add_u32_e32 v244, s0, v211
	v_add_u32_e32 v245, s0, v210
	s_movk_i32 s0, 0x17f
	v_cmp_lt_u32_e32 vcc, s0, v147
	s_nop 1
	v_cndmask_b32_e32 v244, v244, v245, vcc
	v_lshl_add_u32 v245, s63, 8, v147
	s_movk_i32 s0, 0x100
	v_cmp_gt_u32_e32 vcc, s0, v147
	s_nop 1
	v_cndmask_b32_e32 v245, v244, v245, vcc
	v_lshlrev_b32_e32 v244, 2, v245
	global_load_dword v246, v244, s[42:43]
	global_load_dword v247, v244, s[82:83]
	global_load_dword v248, v244, s[86:87]
	global_load_dword v249, v244, s[80:81]
	v_readlane_b32 s6, v252, 47
	v_readlane_b32 s7, v252, 48
	s_nop 4
	global_load_dword v250, v244, s[6:7]
	v_lshl_or_b32 v251, s63, 2, v214
	v_or_b32_e32 v251, s11, v251
	v_lshlrev_b32_e32 v251, 2, v251
	v_readlane_b32 s6, v252, 43
	v_readlane_b32 s7, v252, 44
	s_nop 4
	global_load_dword v241, v251, s[6:7]
	v_readlane_b32 s6, v252, 45
	v_readlane_b32 s7, v252, 46
	s_nop 4
	global_load_dword v251, v251, s[6:7]
	s_waitcnt lgkmcnt(0)
	s_barrier
	s_movk_i32 s0, 0x5000
	v_lshl_add_u32 v244, v147, 2, s0
	s_waitcnt vmcnt(0)
	ds_write_b32 v244, v246
	ds_write_b32 v244, v247 offset:2048
	ds_write_b32 v244, v248 offset:4096
	ds_write_b32 v244, v249 offset:6144
	ds_write_b32 v244, v250 offset:8192
	ds_write_b32 v244, v241 offset:10240
	ds_write_b32 v244, v251 offset:12288
	v_readlane_b32 s22, v252, 12
	v_readlane_b32 s23, v252, 13
	s_ashr_i32 s0, s62, 3
	s_add_i32 s0, s0, s8
	s_mul_i32 s0, s0, 0xc000
	s_add_u32 s6, s22, s0
	s_addc_u32 s7, s23, 0
	v_lshlrev_b32_e32 v244, 2, v245
	global_load_dword v246, v244, s[6:7]
	s_add_u32 s6, s6, 0x4000
	s_addc_u32 s7, s7, 0
	global_load_dword v247, v244, s[6:7]
	s_add_u32 s6, s6, 0x4000
	s_addc_u32 s7, s7, 0
	global_load_dword v248, v244, s[6:7]
	s_and_b32 s21, s62, -8
	s_mul_i32 s22, s21, 0x3000
	s_movk_i32 s23, 0x1000
	v_lshl_add_u32 v244, v245, 1, s23
	s_add_i32 s23, s22, 0xc000000
	s_add_u32 s6, s4, s23
	s_addc_u32 s7, s5, 0
	global_load_ushort v249, v244, s[6:7]
	s_add_i32 s23, s22, 0xc003000
	s_add_u32 s6, s4, s23
	s_addc_u32 s7, s5, 0
	global_load_ushort v250, v244, s[6:7]
	s_add_i32 s23, s22, 0xc006000
	s_add_u32 s6, s4, s23
	s_addc_u32 s7, s5, 0
	global_load_ushort v251, v244, s[6:7]
	s_add_i32 s23, s22, 0xc009000
	s_add_u32 s6, s4, s23
	s_addc_u32 s7, s5, 0
	global_load_ushort v241, v244, s[6:7]
	s_add_i32 s23, s22, 0xc00c000
	s_add_u32 s6, s4, s23
	s_addc_u32 s7, s5, 0
	global_load_ushort v216, v244, s[6:7]
	s_add_i32 s23, s22, 0xc00f000
	s_add_u32 s6, s4, s23
	s_addc_u32 s7, s5, 0
	global_load_ushort v217, v244, s[6:7]
	s_add_i32 s23, s22, 0xc012000
	s_add_u32 s6, s4, s23
	s_addc_u32 s7, s5, 0
	global_load_ushort v218, v244, s[6:7]
	s_add_i32 s23, s22, 0xc015000
	s_add_u32 s6, s4, s23
	s_addc_u32 s7, s5, 0
	global_load_ushort v242, v244, s[6:7]
	s_add_i32 s1, s21, 0x4000
	s_and_b32 s0, s62, 7
	v_add_u32_e32 v243, s1, v213
	v_lshlrev_b32_e32 v243, 7, v243
	v_lshl_or_b32 v244, s0, 2, v214
	v_lshl_add_u32 v243, v244, 2, v243
	v_readlane_b32 s6, v255, 8
	v_readlane_b32 s7, v255, 9
	s_nop 4
	global_load_dword v243, v243, s[6:7]
	s_waitcnt vmcnt(0)
	s_branch .LBB0_827

.LBB0_826:
	s_waitcnt lgkmcnt(0)
	s_barrier
	ds_read_b128 v[150:153], v49 offset:16384
	ds_read_b128 v[138:141], v49 offset:16400
	ds_read_b128 v[70:73], v49 offset:16416
	ds_read_b128 v[66:69], v49 offset:16432
	ds_read_b128 v[162:165], v49 offset:16512
	ds_read2st64_b32 v[154:155], v201 offset1:1
	s_lshl_b32 s7, s63, 2
	s_lshl_b64 s[0:1], s[0:1], 20
	s_add_u32 s0, s34, s0
	s_waitcnt lgkmcnt(1)
	v_mov_b32_e32 v182, v165
	s_waitcnt lgkmcnt(0)
	v_mul_f32_e32 v174, v150, v154
	v_mul_f32_e32 v176, v151, v155
	ds_read2st64_b32 v[150:151], v201 offset0:2 offset1:3
	ds_read_b128 v[166:169], v215 offset:8192
	ds_read_b128 v[170:173], v215 offset:12288
	s_addc_u32 s1, s35, s1
	s_lshl_b32 s21, s63, 17
	v_ashrrev_i32_e32 v149, 31, v148
	s_waitcnt lgkmcnt(2)
	v_mul_f32_e32 v178, v152, v150
	v_mul_f32_e32 v180, v153, v151
	s_waitcnt lgkmcnt(1)
	v_pk_mul_f32 v[150:151], v[174:175], v[168:169] op_sel_hi:[0,1]
	v_pk_mul_f32 v[152:153], v[174:175], v[166:167] op_sel_hi:[0,1]
	v_pk_fma_f32 v[150:151], v[124:125], v[162:163], v[150:151] op_sel_hi:[1,0,1]
	v_pk_fma_f32 v[152:153], v[122:123], v[162:163], v[152:153] op_sel_hi:[1,0,1]
	s_waitcnt lgkmcnt(0)
	v_mul_f32_e32 v123, v173, v151
	v_mul_f32_e32 v122, v171, v153
	v_fmac_f32_e32 v122, v170, v152
	v_fmac_f32_e32 v123, v172, v150
	v_add_f32_e32 v122, v122, v123
	v_add_f32_e32 v175, 0, v122
	v_pk_mul_f32 v[122:123], v[168:169], v[176:177] op_sel_hi:[1,0]
	v_pk_mul_f32 v[124:125], v[166:167], v[176:177] op_sel_hi:[1,0]
	v_pk_fma_f32 v[154:155], v[128:129], v[162:163], v[122:123] op_sel:[0,1,0]
	v_pk_fma_f32 v[156:157], v[126:127], v[162:163], v[124:125] op_sel:[0,1,0]
	v_mul_f32_e32 v123, v173, v155
	v_mul_f32_e32 v122, v171, v157
	v_fmac_f32_e32 v122, v170, v156
	v_fmac_f32_e32 v123, v172, v154
	v_add_f32_e32 v122, v122, v123
	v_add_f32_e32 v177, 0, v122
	v_pk_mul_f32 v[122:123], v[168:169], v[178:179] op_sel_hi:[1,0]
	v_pk_mul_f32 v[124:125], v[166:167], v[178:179] op_sel_hi:[1,0]
	v_pk_fma_f32 v[158:159], v[132:133], v[164:165], v[122:123] op_sel_hi:[1,0,1]
	v_pk_fma_f32 v[160:161], v[130:131], v[164:165], v[124:125] op_sel_hi:[1,0,1]
	v_mul_f32_e32 v123, v173, v159
	v_mul_f32_e32 v122, v171, v161
	v_fmac_f32_e32 v122, v170, v160
	v_fmac_f32_e32 v123, v172, v158
	v_add_f32_e32 v122, v122, v123
	v_add_f32_e32 v179, 0, v122
	v_pk_mul_f32 v[122:123], v[168:169], v[180:181] op_sel_hi:[1,0]
	v_pk_mul_f32 v[124:125], v[166:167], v[180:181] op_sel_hi:[1,0]
	v_pk_fma_f32 v[136:137], v[136:137], v[182:183], v[122:123] op_sel_hi:[1,0,1]
	v_pk_fma_f32 v[134:135], v[134:135], v[182:183], v[124:125] op_sel_hi:[1,0,1]
	v_mul_f32_e32 v123, v173, v137
	v_mul_f32_e32 v122, v171, v135
	v_fmac_f32_e32 v122, v170, v134
	v_fmac_f32_e32 v123, v172, v136
	ds_read_b128 v[166:169], v215 offset:8320
	ds_read_b128 v[170:173], v215 offset:12416
	v_add_f32_e32 v122, v122, v123
	v_add_f32_e32 v165, 0, v122
	s_add_u32 s0, s0, s21
	s_waitcnt lgkmcnt(1)
	v_pk_mul_f32 v[122:123], v[174:175], v[168:169] op_sel_hi:[0,1]
	v_pk_mul_f32 v[124:125], v[174:175], v[166:167] op_sel_hi:[0,1]
	v_pk_fma_f32 v[130:131], v[108:109], v[162:163], v[122:123] op_sel_hi:[1,0,1]
	v_pk_fma_f32 v[132:133], v[106:107], v[162:163], v[124:125] op_sel_hi:[1,0,1]
	s_waitcnt lgkmcnt(0)
	v_mul_f32_e32 v107, v173, v131
	v_mul_f32_e32 v106, v171, v133
	v_fmac_f32_e32 v106, v170, v132
	v_fmac_f32_e32 v107, v172, v130
	v_add_f32_e32 v106, v106, v107
	v_add_f32_e32 v175, v175, v106
	v_pk_mul_f32 v[106:107], v[176:177], v[168:169] op_sel_hi:[0,1]
	v_pk_mul_f32 v[108:109], v[176:177], v[166:167] op_sel_hi:[0,1]
	v_pk_fma_f32 v[126:127], v[112:113], v[162:163], v[106:107] op_sel:[0,1,0]
	v_pk_fma_f32 v[128:129], v[110:111], v[162:163], v[108:109] op_sel:[0,1,0]
	v_mul_f32_e32 v107, v173, v127
	v_mul_f32_e32 v106, v171, v129
	v_fmac_f32_e32 v106, v170, v128
	v_fmac_f32_e32 v107, v172, v126
	v_add_f32_e32 v106, v106, v107
	v_add_f32_e32 v177, v177, v106
	v_pk_mul_f32 v[106:107], v[178:179], v[168:169] op_sel_hi:[0,1]
	v_pk_mul_f32 v[108:109], v[178:179], v[166:167] op_sel_hi:[0,1]
	v_pk_fma_f32 v[122:123], v[116:117], v[164:165], v[106:107] op_sel_hi:[1,0,1]
	v_pk_fma_f32 v[124:125], v[114:115], v[164:165], v[108:109] op_sel_hi:[1,0,1]
	v_mul_f32_e32 v107, v173, v123
	v_mul_f32_e32 v106, v171, v125
	v_fmac_f32_e32 v106, v170, v124
	v_fmac_f32_e32 v107, v172, v122
	v_add_f32_e32 v106, v106, v107
	v_add_f32_e32 v179, v179, v106
	v_pk_mul_f32 v[106:107], v[168:169], v[180:181] op_sel_hi:[1,0]
	v_pk_mul_f32 v[108:109], v[166:167], v[180:181] op_sel_hi:[1,0]
	v_pk_fma_f32 v[114:115], v[120:121], v[182:183], v[106:107] op_sel_hi:[1,0,1]
	v_pk_fma_f32 v[116:117], v[118:119], v[182:183], v[108:109] op_sel_hi:[1,0,1]
	ds_read_b128 v[118:121], v215 offset:8448
	ds_read_b128 v[166:169], v215 offset:12544
	v_mul_f32_e32 v106, v171, v117
	v_mul_f32_e32 v107, v173, v115
	v_fmac_f32_e32 v106, v170, v116
	v_fmac_f32_e32 v107, v172, v114
	v_add_f32_e32 v106, v106, v107
	v_add_f32_e32 v165, v106, v165
	s_waitcnt lgkmcnt(1)
	v_pk_mul_f32 v[106:107], v[174:175], v[120:121] op_sel_hi:[0,1]
	v_pk_mul_f32 v[108:109], v[174:175], v[118:119] op_sel_hi:[0,1]
	v_pk_fma_f32 v[106:107], v[92:93], v[162:163], v[106:107] op_sel_hi:[1,0,1]
	v_pk_fma_f32 v[108:109], v[90:91], v[162:163], v[108:109] op_sel_hi:[1,0,1]
	s_waitcnt lgkmcnt(0)
	v_mul_f32_e32 v91, v169, v107
	v_mul_f32_e32 v90, v167, v109
	v_fmac_f32_e32 v90, v166, v108
	v_fmac_f32_e32 v91, v168, v106
	v_add_f32_e32 v90, v90, v91
	v_add_f32_e32 v170, v175, v90
	v_pk_mul_f32 v[90:91], v[176:177], v[120:121] op_sel_hi:[0,1]
	v_pk_mul_f32 v[92:93], v[176:177], v[118:119] op_sel_hi:[0,1]
	v_pk_fma_f32 v[110:111], v[96:97], v[162:163], v[90:91] op_sel:[0,1,0]
	v_pk_fma_f32 v[112:113], v[94:95], v[162:163], v[92:93] op_sel:[0,1,0]
	v_mul_f32_e32 v91, v169, v111
	v_mul_f32_e32 v90, v167, v113
	v_fmac_f32_e32 v90, v166, v112
	v_fmac_f32_e32 v91, v168, v110
	v_add_f32_e32 v90, v90, v91
	v_add_f32_e32 v171, v177, v90
	v_pk_mul_f32 v[90:91], v[178:179], v[120:121] op_sel_hi:[0,1]
	v_pk_mul_f32 v[92:93], v[178:179], v[118:119] op_sel_hi:[0,1]
	v_pk_fma_f32 v[100:101], v[100:101], v[164:165], v[90:91] op_sel_hi:[1,0,1]
	v_pk_fma_f32 v[98:99], v[98:99], v[164:165], v[92:93] op_sel_hi:[1,0,1]
	v_mul_f32_e32 v91, v169, v101
	v_mul_f32_e32 v90, v167, v99
	v_fmac_f32_e32 v90, v166, v98
	v_fmac_f32_e32 v91, v168, v100
	v_add_f32_e32 v90, v90, v91
	v_add_f32_e32 v172, v179, v90
	v_pk_mul_f32 v[90:91], v[180:181], v[120:121] op_sel_hi:[0,1]
	v_pk_mul_f32 v[92:93], v[180:181], v[118:119] op_sel_hi:[0,1]
	v_pk_fma_f32 v[104:105], v[104:105], v[182:183], v[90:91] op_sel_hi:[1,0,1]
	v_pk_fma_f32 v[102:103], v[102:103], v[182:183], v[92:93] op_sel_hi:[1,0,1]
	v_mul_f32_e32 v91, v169, v105
	v_mul_f32_e32 v90, v167, v103
	v_fmac_f32_e32 v90, v166, v102
	v_fmac_f32_e32 v91, v168, v104
	ds_read_b128 v[118:121], v215 offset:8576
	ds_read_b128 v[166:169], v215 offset:12672
	v_add_f32_e32 v90, v90, v91
	v_add_f32_e32 v165, v165, v90
	s_addc_u32 s1, s1, 0
	s_waitcnt lgkmcnt(1)
	v_pk_mul_f32 v[90:91], v[174:175], v[120:121] op_sel_hi:[0,1]
	v_pk_mul_f32 v[92:93], v[174:175], v[118:119] op_sel_hi:[0,1]
	v_pk_fma_f32 v[94:95], v[76:77], v[162:163], v[90:91] op_sel_hi:[1,0,1]
	v_pk_fma_f32 v[96:97], v[74:75], v[162:163], v[92:93] op_sel_hi:[1,0,1]
	s_waitcnt lgkmcnt(0)
	v_mul_f32_e32 v75, v169, v95
	v_mul_f32_e32 v74, v167, v97
	v_fmac_f32_e32 v74, v166, v96
	v_fmac_f32_e32 v75, v168, v94
	v_add_f32_e32 v74, v74, v75
	v_add_f32_e32 v170, v170, v74
	v_pk_mul_f32 v[74:75], v[176:177], v[120:121] op_sel_hi:[0,1]
	v_pk_mul_f32 v[76:77], v[176:177], v[118:119] op_sel_hi:[0,1]
	v_pk_fma_f32 v[90:91], v[80:81], v[162:163], v[74:75] op_sel:[0,1,0]
	v_pk_fma_f32 v[92:93], v[78:79], v[162:163], v[76:77] op_sel:[0,1,0]
	v_mul_f32_e32 v75, v169, v91
	v_mul_f32_e32 v74, v167, v93
	v_fmac_f32_e32 v74, v166, v92
	v_fmac_f32_e32 v75, v168, v90
	v_add_f32_e32 v74, v74, v75
	v_add_f32_e32 v162, v171, v74
	v_pk_mul_f32 v[74:75], v[178:179], v[120:121] op_sel_hi:[0,1]
	v_pk_mul_f32 v[76:77], v[178:179], v[118:119] op_sel_hi:[0,1]
	v_pk_fma_f32 v[84:85], v[84:85], v[164:165], v[74:75] op_sel_hi:[1,0,1]
	v_pk_fma_f32 v[82:83], v[82:83], v[164:165], v[76:77] op_sel_hi:[1,0,1]
	v_mul_f32_e32 v75, v169, v85
	v_mul_f32_e32 v74, v167, v83
	v_fmac_f32_e32 v74, v166, v82
	v_fmac_f32_e32 v75, v168, v84
	v_add_f32_e32 v74, v74, v75
	v_add_f32_e32 v163, v172, v74
	v_pk_mul_f32 v[74:75], v[180:181], v[120:121] op_sel_hi:[0,1]
	v_pk_mul_f32 v[76:77], v[180:181], v[118:119] op_sel_hi:[0,1]
	v_pk_fma_f32 v[78:79], v[88:89], v[182:183], v[74:75] op_sel_hi:[1,0,1]
	v_pk_fma_f32 v[80:81], v[86:87], v[182:183], v[76:77] op_sel_hi:[1,0,1]
	v_mul_f32_e32 v75, v169, v79
	v_mul_f32_e32 v74, v167, v81
	v_fmac_f32_e32 v74, v166, v80
	v_fmac_f32_e32 v75, v168, v78
	v_add_f32_e32 v74, v74, v75
	s_nop 1
	v_add_f32_e32 v74, v165, v74
	s_or_b32 s64, s7, s11
	v_readlane_b32 s24, v252, 53
	v_readlane_b32 s25, v252, 54
	s_waitcnt lgkmcnt(0)
	v_add_f32_dpp v75, v170, v170 quad_perm:[1,0,3,2] row_mask:0xf bank_mask:0xf
	s_nop 1
	v_readlane_b32 s26, v252, 55
	v_readlane_b32 s27, v252, 56
	s_waitcnt lgkmcnt(0)
	v_add_f32_dpp v75, v75, v75 quad_perm:[2,3,0,1] row_mask:0xf bank_mask:0xf
	s_nop 1
	s_waitcnt lgkmcnt(0)
	v_add_f32_dpp v75, v75, v75 row_half_mirror row_mask:0xf bank_mask:0xf
	v_cndmask_b32_e64 v121, 0, v75, s[46:47]
	s_nop 1
	s_waitcnt lgkmcnt(0)
	v_add_f32_dpp v75, v162, v162 quad_perm:[1,0,3,2] row_mask:0xf bank_mask:0xf
	s_nop 1
	s_waitcnt lgkmcnt(0)
	v_add_f32_dpp v75, v75, v75 quad_perm:[2,3,0,1] row_mask:0xf bank_mask:0xf
	s_nop 1
	s_waitcnt lgkmcnt(0)
	v_add_f32_dpp v75, v75, v75 row_half_mirror row_mask:0xf bank_mask:0xf
	v_cndmask_b32_e64 v119, 0, v75, s[46:47]
	s_nop 1
	s_waitcnt lgkmcnt(0)
	v_add_f32_dpp v75, v163, v163 quad_perm:[1,0,3,2] row_mask:0xf bank_mask:0xf
	s_nop 1
	s_waitcnt lgkmcnt(0)
	v_add_f32_dpp v75, v75, v75 quad_perm:[2,3,0,1] row_mask:0xf bank_mask:0xf
	s_nop 1
	s_waitcnt lgkmcnt(0)
	v_add_f32_dpp v75, v75, v75 row_half_mirror row_mask:0xf bank_mask:0xf
	v_cndmask_b32_e64 v89, 0, v75, s[46:47]
	s_nop 1
	s_waitcnt lgkmcnt(0)
	v_add_f32_dpp v74, v74, v74 quad_perm:[1,0,3,2] row_mask:0xf bank_mask:0xf
	s_nop 1
	s_waitcnt lgkmcnt(0)
	v_add_f32_dpp v74, v74, v74 quad_perm:[2,3,0,1] row_mask:0xf bank_mask:0xf
	s_nop 1
	s_waitcnt lgkmcnt(0)
	v_add_f32_dpp v74, v74, v74 row_half_mirror row_mask:0xf bank_mask:0xf
	v_cndmask_b32_e64 v87, 0, v74, s[46:47]
	ds_read_b128 v[74:77], v49 offset:16528
	ds_read2st64_b32 v[162:163], v201 offset0:4 offset1:5
	s_waitcnt lgkmcnt(1)
	v_mov_b32_e32 v176, v77
	s_waitcnt lgkmcnt(0)
	v_mul_f32_e32 v120, v138, v162
	v_mul_f32_e32 v88, v139, v163
	ds_read2st64_b32 v[138:139], v201 offset0:6 offset1:7
	ds_read_b128 v[162:165], v215 offset:8704
	ds_read_b128 v[166:169], v215 offset:12800
	ds_read_b128 v[172:175], v215 offset:8832
	ds_read_b128 v[178:181], v215 offset:12928
	s_waitcnt lgkmcnt(4)
	v_mul_f32_e32 v118, v140, v138
	v_mul_f32_e32 v86, v141, v139
	s_waitcnt lgkmcnt(3)
	v_pk_mul_f32 v[138:139], v[120:121], v[164:165] op_sel_hi:[0,1]
	v_pk_mul_f32 v[140:141], v[120:121], v[162:163] op_sel_hi:[0,1]
	v_pk_fma_f32 v[138:139], v[150:151], v[74:75], v[138:139] op_sel_hi:[1,0,1]
	v_pk_fma_f32 v[140:141], v[152:153], v[74:75], v[140:141] op_sel_hi:[1,0,1]
	s_waitcnt lgkmcnt(2)
	v_mul_f32_e32 v151, v169, v139
	v_mul_f32_e32 v150, v167, v141
	v_fmac_f32_e32 v150, v166, v140
	v_fmac_f32_e32 v151, v168, v138
	v_add_f32_e32 v150, v150, v151
	v_add_f32_e32 v170, 0, v150
	v_pk_mul_f32 v[150:151], v[164:165], v[88:89] op_sel_hi:[1,0]
	v_pk_mul_f32 v[152:153], v[162:163], v[88:89] op_sel_hi:[1,0]
	v_pk_fma_f32 v[150:151], v[154:155], v[74:75], v[150:151] op_sel:[0,1,0]
	v_pk_fma_f32 v[152:153], v[156:157], v[74:75], v[152:153] op_sel:[0,1,0]
	v_mul_f32_e32 v155, v169, v151
	v_mul_f32_e32 v154, v167, v153
	v_fmac_f32_e32 v154, v166, v152
	v_fmac_f32_e32 v155, v168, v150
	v_add_f32_e32 v154, v154, v155
	v_add_f32_e32 v171, 0, v154
	v_pk_mul_f32 v[154:155], v[164:165], v[118:119] op_sel_hi:[1,0]
	v_pk_mul_f32 v[156:157], v[162:163], v[118:119] op_sel_hi:[1,0]
	v_pk_fma_f32 v[154:155], v[158:159], v[76:77], v[154:155] op_sel_hi:[1,0,1]
	v_pk_fma_f32 v[156:157], v[160:161], v[76:77], v[156:157] op_sel_hi:[1,0,1]
	v_mul_f32_e32 v159, v169, v155
	v_mul_f32_e32 v158, v167, v157
	v_fmac_f32_e32 v158, v166, v156
	v_fmac_f32_e32 v159, v168, v154
	v_add_f32_e32 v158, v158, v159
	v_add_f32_e32 v177, 0, v158
	v_pk_mul_f32 v[158:159], v[164:165], v[86:87] op_sel_hi:[1,0]
	v_pk_mul_f32 v[160:161], v[162:163], v[86:87] op_sel_hi:[1,0]
	v_pk_fma_f32 v[136:137], v[136:137], v[176:177], v[158:159] op_sel_hi:[1,0,1]
	v_pk_fma_f32 v[158:159], v[134:135], v[176:177], v[160:161] op_sel_hi:[1,0,1]
	v_mul_f32_e32 v134, v169, v137
	v_mul_f32_e32 v77, v167, v159
	v_fmac_f32_e32 v77, v166, v158
	v_fmac_f32_e32 v134, v168, v136
	v_add_f32_e32 v77, v77, v134
	s_waitcnt lgkmcnt(1)
	v_pk_mul_f32 v[134:135], v[120:121], v[174:175] op_sel_hi:[0,1]
	v_pk_mul_f32 v[162:163], v[120:121], v[172:173] op_sel_hi:[0,1]
	v_pk_fma_f32 v[160:161], v[130:131], v[74:75], v[134:135] op_sel_hi:[1,0,1]
	v_pk_fma_f32 v[162:163], v[132:133], v[74:75], v[162:163] op_sel_hi:[1,0,1]
	s_waitcnt lgkmcnt(0)
	v_mul_f32_e32 v131, v181, v161
	v_mul_f32_e32 v130, v179, v163
	v_fmac_f32_e32 v130, v178, v162
	v_fmac_f32_e32 v131, v180, v160
	v_add_f32_e32 v130, v130, v131
	v_add_f32_e32 v134, v170, v130
	v_pk_mul_f32 v[130:131], v[88:89], v[174:175] op_sel_hi:[0,1]
	v_pk_mul_f32 v[132:133], v[88:89], v[172:173] op_sel_hi:[0,1]
	v_pk_fma_f32 v[164:165], v[126:127], v[74:75], v[130:131] op_sel:[0,1,0]
	v_pk_fma_f32 v[166:167], v[128:129], v[74:75], v[132:133] op_sel:[0,1,0]
	v_mul_f32_e32 v127, v181, v165
	v_mul_f32_e32 v126, v179, v167
	v_fmac_f32_e32 v126, v178, v166
	v_fmac_f32_e32 v127, v180, v164
	v_add_f32_e32 v126, v126, v127
	v_add_f32_e32 v77, 0, v77
	v_add_f32_e32 v130, v171, v126
	v_pk_mul_f32 v[126:127], v[118:119], v[174:175] op_sel_hi:[0,1]
	v_pk_mul_f32 v[128:129], v[118:119], v[172:173] op_sel_hi:[0,1]
	v_pk_fma_f32 v[168:169], v[122:123], v[76:77], v[126:127] op_sel_hi:[1,0,1]
	v_pk_fma_f32 v[170:171], v[124:125], v[76:77], v[128:129] op_sel_hi:[1,0,1]
	v_mul_f32_e32 v123, v181, v169
	v_mul_f32_e32 v122, v179, v171
	v_fmac_f32_e32 v122, v178, v170
	v_fmac_f32_e32 v123, v180, v168
	v_add_f32_e32 v122, v122, v123
	v_add_f32_e32 v131, v177, v122
	v_pk_mul_f32 v[122:123], v[174:175], v[86:87] op_sel_hi:[1,0]
	v_pk_mul_f32 v[124:125], v[172:173], v[86:87] op_sel_hi:[1,0]
	v_pk_fma_f32 v[172:173], v[114:115], v[176:177], v[122:123] op_sel_hi:[1,0,1]
	v_pk_fma_f32 v[174:175], v[116:117], v[176:177], v[124:125] op_sel_hi:[1,0,1]
	v_mul_f32_e32 v115, v181, v173
	v_mul_f32_e32 v114, v179, v175
	v_fmac_f32_e32 v114, v178, v174
	v_fmac_f32_e32 v115, v180, v172
	v_add_f32_e32 v114, v114, v115
	v_add_f32_e32 v77, v114, v77
	ds_read_b128 v[114:117], v215 offset:8960
	ds_read_b128 v[122:125], v215 offset:13056
	s_waitcnt lgkmcnt(1)
	v_pk_mul_f32 v[126:127], v[120:121], v[116:117] op_sel_hi:[0,1]
	v_pk_mul_f32 v[128:129], v[120:121], v[114:115] op_sel_hi:[0,1]
	v_pk_fma_f32 v[178:179], v[106:107], v[74:75], v[126:127] op_sel_hi:[1,0,1]
	v_pk_fma_f32 v[180:181], v[108:109], v[74:75], v[128:129] op_sel_hi:[1,0,1]
	s_waitcnt lgkmcnt(0)
	v_mul_f32_e32 v107, v125, v179
	v_mul_f32_e32 v106, v123, v181
	v_fmac_f32_e32 v106, v122, v180
	v_fmac_f32_e32 v107, v124, v178
	v_add_f32_e32 v106, v106, v107
	v_add_f32_e32 v126, v134, v106
	v_pk_mul_f32 v[106:107], v[88:89], v[116:117] op_sel_hi:[0,1]
	v_pk_mul_f32 v[108:109], v[88:89], v[114:115] op_sel_hi:[0,1]
	v_pk_fma_f32 v[182:183], v[110:111], v[74:75], v[106:107] op_sel:[0,1,0]
	v_pk_fma_f32 v[184:185], v[112:113], v[74:75], v[108:109] op_sel:[0,1,0]
	v_mul_f32_e32 v107, v125, v183
	v_mul_f32_e32 v106, v123, v185
	v_fmac_f32_e32 v106, v122, v184
	v_fmac_f32_e32 v107, v124, v182
	v_add_f32_e32 v106, v106, v107
	v_add_f32_e32 v127, v130, v106
	v_pk_mul_f32 v[106:107], v[118:119], v[116:117] op_sel_hi:[0,1]
	v_pk_mul_f32 v[108:109], v[118:119], v[114:115] op_sel_hi:[0,1]
	v_pk_fma_f32 v[100:101], v[100:101], v[76:77], v[106:107] op_sel_hi:[1,0,1]
	v_pk_fma_f32 v[186:187], v[98:99], v[76:77], v[108:109] op_sel_hi:[1,0,1]
	v_mul_f32_e32 v99, v125, v101
	v_mul_f32_e32 v98, v123, v187
	v_fmac_f32_e32 v98, v122, v186
	v_fmac_f32_e32 v99, v124, v100
	v_add_f32_e32 v98, v98, v99
	v_add_f32_e32 v128, v131, v98
	v_pk_mul_f32 v[98:99], v[86:87], v[116:117] op_sel_hi:[0,1]
	v_pk_mul_f32 v[106:107], v[86:87], v[114:115] op_sel_hi:[0,1]
	v_pk_fma_f32 v[104:105], v[104:105], v[176:177], v[98:99] op_sel_hi:[1,0,1]
	v_pk_fma_f32 v[188:189], v[102:103], v[176:177], v[106:107] op_sel_hi:[1,0,1]
	ds_read_b128 v[106:109], v215 offset:9088
	ds_read_b128 v[110:113], v215 offset:13184
	v_mul_f32_e32 v98, v123, v189
	v_mul_f32_e32 v99, v125, v105
	v_fmac_f32_e32 v98, v122, v188
	v_fmac_f32_e32 v99, v124, v104
	v_add_f32_e32 v98, v98, v99
	v_add_f32_e32 v114, v77, v98
	s_waitcnt lgkmcnt(1)
	v_pk_mul_f32 v[98:99], v[120:121], v[108:109] op_sel_hi:[0,1]
	v_pk_mul_f32 v[102:103], v[120:121], v[106:107] op_sel_hi:[0,1]
	v_pk_fma_f32 v[190:191], v[94:95], v[74:75], v[98:99] op_sel_hi:[1,0,1]
	v_pk_fma_f32 v[192:193], v[96:97], v[74:75], v[102:103] op_sel_hi:[1,0,1]
	s_waitcnt lgkmcnt(0)
	v_mul_f32_e32 v94, v113, v191
	v_mul_f32_e32 v77, v111, v193
	v_fmac_f32_e32 v77, v110, v192
	v_fmac_f32_e32 v94, v112, v190
	v_add_f32_e32 v77, v77, v94
	v_pk_mul_f32 v[94:95], v[88:89], v[108:109] op_sel_hi:[0,1]
	v_pk_mul_f32 v[96:97], v[88:89], v[106:107] op_sel_hi:[0,1]
	v_pk_fma_f32 v[194:195], v[90:91], v[74:75], v[94:95] op_sel:[0,1,0]
	v_pk_fma_f32 v[74:75], v[92:93], v[74:75], v[96:97] op_sel:[0,1,0]
	v_add_f32_e32 v98, v126, v77
	v_mul_f32_e32 v77, v111, v75
	v_mul_f32_e32 v88, v113, v195
	v_fmac_f32_e32 v77, v110, v74
	v_fmac_f32_e32 v88, v112, v194
	v_add_f32_e32 v77, v77, v88
	v_pk_mul_f32 v[90:91], v[118:119], v[108:109] op_sel_hi:[0,1]
	v_pk_mul_f32 v[92:93], v[118:119], v[106:107] op_sel_hi:[0,1]
	v_add_f32_e32 v88, v127, v77
	v_pk_fma_f32 v[196:197], v[84:85], v[76:77], v[90:91] op_sel_hi:[1,0,1]
	v_pk_fma_f32 v[76:77], v[82:83], v[76:77], v[92:93] op_sel_hi:[1,0,1]
	v_mul_f32_e32 v83, v113, v197
	v_mul_f32_e32 v82, v111, v77
	v_fmac_f32_e32 v82, v110, v76
	v_fmac_f32_e32 v83, v112, v196
	v_add_f32_e32 v82, v82, v83
	v_add_f32_e32 v90, v128, v82
	v_pk_mul_f32 v[82:83], v[86:87], v[108:109] op_sel_hi:[0,1]
	v_pk_mul_f32 v[84:85], v[86:87], v[106:107] op_sel_hi:[0,1]
	v_pk_fma_f32 v[198:199], v[78:79], v[176:177], v[82:83] op_sel_hi:[1,0,1]
	v_pk_fma_f32 v[176:177], v[80:81], v[176:177], v[84:85] op_sel_hi:[1,0,1]
	v_mul_f32_e32 v79, v113, v199
	v_mul_f32_e32 v78, v111, v177
	v_fmac_f32_e32 v78, v110, v176
	v_fmac_f32_e32 v79, v112, v198
	v_add_f32_e32 v78, v78, v79
	s_nop 1
	v_add_f32_e32 v78, v114, v78
	s_waitcnt lgkmcnt(0)
	v_add_f32_dpp v79, v98, v98 quad_perm:[1,0,3,2] row_mask:0xf bank_mask:0xf
	s_nop 1
	s_waitcnt lgkmcnt(0)
	v_add_f32_dpp v79, v79, v79 quad_perm:[2,3,0,1] row_mask:0xf bank_mask:0xf
	s_nop 1
	s_waitcnt lgkmcnt(0)
	v_add_f32_dpp v79, v79, v79 row_half_mirror row_mask:0xf bank_mask:0xf
	v_cndmask_b32_e64 v225, v121, v79, s[48:49]
	s_nop 1
	s_waitcnt lgkmcnt(0)
	v_add_f32_dpp v79, v88, v88 quad_perm:[1,0,3,2] row_mask:0xf bank_mask:0xf
	s_nop 1
	s_waitcnt lgkmcnt(0)
	v_add_f32_dpp v79, v79, v79 quad_perm:[2,3,0,1] row_mask:0xf bank_mask:0xf
	s_nop 1
	s_waitcnt lgkmcnt(0)
	v_add_f32_dpp v79, v79, v79 row_half_mirror row_mask:0xf bank_mask:0xf
	v_cndmask_b32_e64 v227, v119, v79, s[48:49]
	s_nop 1
	s_waitcnt lgkmcnt(0)
	v_add_f32_dpp v79, v90, v90 quad_perm:[1,0,3,2] row_mask:0xf bank_mask:0xf
	s_nop 1
	s_waitcnt lgkmcnt(0)
	v_add_f32_dpp v79, v79, v79 quad_perm:[2,3,0,1] row_mask:0xf bank_mask:0xf
	s_nop 1
	s_waitcnt lgkmcnt(0)
	v_add_f32_dpp v79, v79, v79 row_half_mirror row_mask:0xf bank_mask:0xf
	v_cndmask_b32_e64 v229, v89, v79, s[48:49]
	s_nop 1
	s_waitcnt lgkmcnt(0)
	v_add_f32_dpp v78, v78, v78 quad_perm:[1,0,3,2] row_mask:0xf bank_mask:0xf
	s_nop 1
	s_waitcnt lgkmcnt(0)
	v_add_f32_dpp v78, v78, v78 quad_perm:[2,3,0,1] row_mask:0xf bank_mask:0xf
	s_nop 1
	s_waitcnt lgkmcnt(0)
	v_add_f32_dpp v78, v78, v78 row_half_mirror row_mask:0xf bank_mask:0xf
	v_cndmask_b32_e64 v230, v87, v78, s[48:49]
	ds_read_b128 v[78:81], v49 offset:16544
	ds_read2st64_b32 v[82:83], v201 offset0:8 offset1:9
	s_waitcnt lgkmcnt(0)
	v_mul_f32_e32 v86, v70, v82
	v_mul_f32_e32 v224, v71, v83
	ds_read2st64_b32 v[70:71], v201 offset0:10 offset1:11
	s_waitcnt lgkmcnt(0)
	v_mul_f32_e32 v226, v72, v70
	v_mul_f32_e32 v228, v73, v71
	ds_read_b128 v[70:73], v215 offset:9216
	ds_read_b128 v[82:85], v215 offset:13312
	s_waitcnt lgkmcnt(1)
	v_pk_mul_f32 v[88:89], v[86:87], v[72:73] op_sel_hi:[0,1]
	v_pk_mul_f32 v[90:91], v[86:87], v[70:71] op_sel_hi:[0,1]
	v_pk_fma_f32 v[122:123], v[138:139], v[78:79], v[88:89] op_sel_hi:[1,0,1]
	v_pk_fma_f32 v[124:125], v[140:141], v[78:79], v[90:91] op_sel_hi:[1,0,1]
	s_waitcnt lgkmcnt(0)
	v_mul_f32_e32 v88, v85, v123
	v_mul_f32_e32 v87, v83, v125
	v_fmac_f32_e32 v87, v82, v124
	v_fmac_f32_e32 v88, v84, v122
	v_add_f32_e32 v87, v87, v88
	v_pk_mul_f32 v[88:89], v[72:73], v[224:225] op_sel_hi:[1,0]
	v_pk_mul_f32 v[90:91], v[70:71], v[224:225] op_sel_hi:[1,0]
	v_pk_fma_f32 v[126:127], v[150:151], v[78:79], v[88:89] op_sel:[0,1,0]
	v_pk_fma_f32 v[128:129], v[152:153], v[78:79], v[90:91] op_sel:[0,1,0]
	v_mul_f32_e32 v89, v85, v127
	v_mul_f32_e32 v88, v83, v129
	v_fmac_f32_e32 v88, v82, v128
	v_fmac_f32_e32 v89, v84, v126
	v_add_f32_e32 v88, v88, v89
	v_add_f32_e32 v92, 0, v88
	v_pk_mul_f32 v[88:89], v[72:73], v[226:227] op_sel_hi:[1,0]
	v_pk_mul_f32 v[90:91], v[70:71], v[226:227] op_sel_hi:[1,0]
	v_pk_mul_f32 v[72:73], v[72:73], v[228:229] op_sel_hi:[1,0]
	v_pk_mul_f32 v[70:71], v[70:71], v[228:229] op_sel_hi:[1,0]
	v_mov_b32_e32 v150, v81
	v_pk_fma_f32 v[134:135], v[136:137], v[150:151], v[72:73] op_sel_hi:[1,0,1]
	v_pk_fma_f32 v[136:137], v[158:159], v[150:151], v[70:71] op_sel_hi:[1,0,1]
	v_mul_f32_e32 v71, v85, v135
	v_mul_f32_e32 v70, v83, v137
	v_pk_fma_f32 v[130:131], v[154:155], v[80:81], v[88:89] op_sel_hi:[1,0,1]
	v_pk_fma_f32 v[132:133], v[156:157], v[80:81], v[90:91] op_sel_hi:[1,0,1]
	v_fmac_f32_e32 v70, v82, v136
	v_fmac_f32_e32 v71, v84, v134
	v_mul_f32_e32 v88, v83, v133
	v_mul_f32_e32 v89, v85, v131
	v_add_f32_e32 v70, v70, v71
	v_fmac_f32_e32 v88, v82, v132
	v_fmac_f32_e32 v89, v84, v130
	v_add_f32_e32 v81, 0, v70
	ds_read_b128 v[70:73], v215 offset:9344
	ds_read_b128 v[82:85], v215 offset:13440
	v_add_f32_e32 v87, 0, v87
	v_add_f32_e32 v88, v88, v89
	v_add_f32_e32 v93, 0, v88
	s_waitcnt lgkmcnt(1)
	v_pk_mul_f32 v[88:89], v[86:87], v[72:73] op_sel_hi:[0,1]
	v_pk_mul_f32 v[90:91], v[86:87], v[70:71] op_sel_hi:[0,1]
	v_pk_fma_f32 v[118:119], v[160:161], v[78:79], v[88:89] op_sel_hi:[1,0,1]
	v_pk_fma_f32 v[120:121], v[162:163], v[78:79], v[90:91] op_sel_hi:[1,0,1]
	s_waitcnt lgkmcnt(0)
	v_mul_f32_e32 v89, v85, v119
	v_mul_f32_e32 v88, v83, v121
	v_fmac_f32_e32 v88, v82, v120
	v_fmac_f32_e32 v89, v84, v118
	v_add_f32_e32 v88, v88, v89
	v_add_f32_e32 v87, v87, v88
	v_pk_mul_f32 v[88:89], v[224:225], v[72:73] op_sel_hi:[0,1]
	v_pk_mul_f32 v[90:91], v[224:225], v[70:71] op_sel_hi:[0,1]
	v_pk_fma_f32 v[114:115], v[164:165], v[78:79], v[88:89] op_sel:[0,1,0]
	v_pk_fma_f32 v[116:117], v[166:167], v[78:79], v[90:91] op_sel:[0,1,0]
	v_mul_f32_e32 v89, v85, v115
	v_mul_f32_e32 v88, v83, v117
	v_fmac_f32_e32 v88, v82, v116
	v_fmac_f32_e32 v89, v84, v114
	v_add_f32_e32 v88, v88, v89
	v_add_f32_e32 v98, v92, v88
	v_pk_mul_f32 v[88:89], v[226:227], v[72:73] op_sel_hi:[0,1]
	v_pk_mul_f32 v[90:91], v[226:227], v[70:71] op_sel_hi:[0,1]
	v_pk_mul_f32 v[72:73], v[72:73], v[228:229] op_sel_hi:[1,0]
	v_pk_mul_f32 v[70:71], v[70:71], v[228:229] op_sel_hi:[1,0]
	v_pk_fma_f32 v[106:107], v[172:173], v[150:151], v[72:73] op_sel_hi:[1,0,1]
	v_pk_fma_f32 v[108:109], v[174:175], v[150:151], v[70:71] op_sel_hi:[1,0,1]
	v_mul_f32_e32 v71, v85, v107
	v_mul_f32_e32 v70, v83, v109
	v_pk_fma_f32 v[110:111], v[168:169], v[80:81], v[88:89] op_sel_hi:[1,0,1]
	v_pk_fma_f32 v[112:113], v[170:171], v[80:81], v[90:91] op_sel_hi:[1,0,1]
	v_fmac_f32_e32 v70, v82, v108
	v_fmac_f32_e32 v71, v84, v106
	v_mul_f32_e32 v88, v83, v113
	v_mul_f32_e32 v89, v85, v111
	v_add_f32_e32 v70, v70, v71
	v_fmac_f32_e32 v88, v82, v112
	v_fmac_f32_e32 v89, v84, v110
	v_add_f32_e32 v81, v70, v81
	ds_read_b128 v[70:73], v215 offset:9472
	ds_read_b128 v[82:85], v215 offset:13568
	v_add_f32_e32 v88, v88, v89
	v_add_f32_e32 v138, v93, v88
	s_waitcnt lgkmcnt(1)
	v_pk_mul_f32 v[88:89], v[86:87], v[72:73] op_sel_hi:[0,1]
	v_pk_mul_f32 v[92:93], v[86:87], v[70:71] op_sel_hi:[0,1]
	v_pk_fma_f32 v[90:91], v[178:179], v[78:79], v[88:89] op_sel_hi:[1,0,1]
	v_pk_fma_f32 v[92:93], v[180:181], v[78:79], v[92:93] op_sel_hi:[1,0,1]
	s_waitcnt lgkmcnt(0)
	v_mul_f32_e32 v89, v85, v91
	v_mul_f32_e32 v88, v83, v93
	v_fmac_f32_e32 v88, v82, v92
	v_fmac_f32_e32 v89, v84, v90
	v_add_f32_e32 v88, v88, v89
	v_add_f32_e32 v151, v87, v88
	v_pk_mul_f32 v[88:89], v[224:225], v[72:73] op_sel_hi:[0,1]
	v_pk_mul_f32 v[96:97], v[224:225], v[70:71] op_sel_hi:[0,1]
	v_pk_fma_f32 v[94:95], v[182:183], v[78:79], v[88:89] op_sel:[0,1,0]
	v_pk_fma_f32 v[96:97], v[184:185], v[78:79], v[96:97] op_sel:[0,1,0]
	v_mul_f32_e32 v88, v85, v95
	v_mul_f32_e32 v87, v83, v97
	v_fmac_f32_e32 v87, v82, v96
	v_fmac_f32_e32 v88, v84, v94
	v_add_f32_e32 v87, v87, v88
	v_pk_mul_f32 v[88:89], v[226:227], v[72:73] op_sel_hi:[0,1]
	v_pk_mul_f32 v[102:103], v[226:227], v[70:71] op_sel_hi:[0,1]
	v_pk_mul_f32 v[72:73], v[228:229], v[72:73] op_sel_hi:[0,1]
	v_pk_mul_f32 v[70:71], v[228:229], v[70:71] op_sel_hi:[0,1]
	v_add_f32_e32 v152, v98, v87
	v_pk_fma_f32 v[98:99], v[100:101], v[80:81], v[88:89] op_sel_hi:[1,0,1]
	v_pk_fma_f32 v[100:101], v[186:187], v[80:81], v[102:103] op_sel_hi:[1,0,1]
	v_pk_fma_f32 v[102:103], v[104:105], v[150:151], v[72:73] op_sel_hi:[1,0,1]
	v_pk_fma_f32 v[104:105], v[188:189], v[150:151], v[70:71] op_sel_hi:[1,0,1]
	v_mul_f32_e32 v87, v83, v101
	v_mul_f32_e32 v88, v85, v99
	v_mul_f32_e32 v70, v83, v105
	v_mul_f32_e32 v71, v85, v103
	v_fmac_f32_e32 v87, v82, v100
	v_fmac_f32_e32 v88, v84, v98
	v_fmac_f32_e32 v70, v82, v104
	v_fmac_f32_e32 v71, v84, v102
	v_add_f32_e32 v87, v87, v88
	v_add_f32_e32 v70, v70, v71
	v_add_f32_e32 v154, v138, v87
	v_add_f32_e32 v155, v81, v70
	ds_read_b128 v[70:73], v215 offset:9600
	ds_read_b128 v[138:141], v215 offset:13696
	s_waitcnt lgkmcnt(1)
	v_pk_mul_f32 v[82:83], v[86:87], v[72:73] op_sel_hi:[0,1]
	v_pk_mul_f32 v[84:85], v[86:87], v[70:71] op_sel_hi:[0,1]
	v_pk_fma_f32 v[86:87], v[190:191], v[78:79], v[82:83] op_sel_hi:[1,0,1]
	v_pk_fma_f32 v[88:89], v[192:193], v[78:79], v[84:85] op_sel_hi:[1,0,1]
	s_waitcnt lgkmcnt(0)
	v_mul_f32_e32 v82, v141, v87
	v_mul_f32_e32 v81, v139, v89
	v_fmac_f32_e32 v81, v138, v88
	v_fmac_f32_e32 v82, v140, v86
	v_add_f32_e32 v81, v81, v82
	v_pk_mul_f32 v[82:83], v[224:225], v[72:73] op_sel_hi:[0,1]
	v_pk_mul_f32 v[84:85], v[224:225], v[70:71] op_sel_hi:[0,1]
	v_pk_fma_f32 v[82:83], v[194:195], v[78:79], v[82:83] op_sel:[0,1,0]
	v_pk_fma_f32 v[84:85], v[74:75], v[78:79], v[84:85] op_sel:[0,1,0]
	v_mul_f32_e32 v75, v141, v83
	v_mul_f32_e32 v74, v139, v85
	v_fmac_f32_e32 v74, v138, v84
	v_fmac_f32_e32 v75, v140, v82
	v_add_f32_e32 v74, v74, v75
	v_add_f32_e32 v156, v152, v74
	v_pk_mul_f32 v[74:75], v[226:227], v[72:73] op_sel_hi:[0,1]
	v_pk_mul_f32 v[152:153], v[226:227], v[70:71] op_sel_hi:[0,1]
	v_add_f32_e32 v151, v151, v81
	v_pk_fma_f32 v[78:79], v[196:197], v[80:81], v[74:75] op_sel_hi:[1,0,1]
	v_pk_fma_f32 v[80:81], v[76:77], v[80:81], v[152:153] op_sel_hi:[1,0,1]
	v_mul_f32_e32 v75, v141, v79
	v_mul_f32_e32 v74, v139, v81
	v_fmac_f32_e32 v74, v138, v80
	v_fmac_f32_e32 v75, v140, v78
	v_add_f32_e32 v74, v74, v75
	v_pk_mul_f32 v[72:73], v[228:229], v[72:73] op_sel_hi:[0,1]
	v_pk_mul_f32 v[70:71], v[228:229], v[70:71] op_sel_hi:[0,1]
	v_add_f32_e32 v152, v154, v74
	v_pk_fma_f32 v[74:75], v[198:199], v[150:151], v[72:73] op_sel_hi:[1,0,1]
	v_pk_fma_f32 v[76:77], v[176:177], v[150:151], v[70:71] op_sel_hi:[1,0,1]
	v_mul_f32_e32 v71, v141, v75
	v_mul_f32_e32 v70, v139, v77
	v_fmac_f32_e32 v70, v138, v76
	v_fmac_f32_e32 v71, v140, v74
	v_add_f32_e32 v70, v70, v71
	s_nop 1
	v_add_f32_e32 v70, v155, v70
	s_waitcnt lgkmcnt(0)
	v_add_f32_dpp v71, v151, v151 quad_perm:[1,0,3,2] row_mask:0xf bank_mask:0xf
	s_nop 1
	s_waitcnt lgkmcnt(0)
	v_add_f32_dpp v71, v71, v71 quad_perm:[2,3,0,1] row_mask:0xf bank_mask:0xf
	s_nop 1
	s_waitcnt lgkmcnt(0)
	v_add_f32_dpp v71, v71, v71 row_half_mirror row_mask:0xf bank_mask:0xf
	v_cndmask_b32_e64 v177, v225, v71, s[50:51]
	s_nop 1
	s_waitcnt lgkmcnt(0)
	v_add_f32_dpp v71, v156, v156 quad_perm:[1,0,3,2] row_mask:0xf bank_mask:0xf
	s_nop 1
	s_waitcnt lgkmcnt(0)
	v_add_f32_dpp v71, v71, v71 quad_perm:[2,3,0,1] row_mask:0xf bank_mask:0xf
	s_nop 1
	s_waitcnt lgkmcnt(0)
	v_add_f32_dpp v71, v71, v71 row_half_mirror row_mask:0xf bank_mask:0xf
	v_cndmask_b32_e64 v176, v227, v71, s[50:51]
	s_nop 1
	s_waitcnt lgkmcnt(0)
	v_add_f32_dpp v71, v152, v152 quad_perm:[1,0,3,2] row_mask:0xf bank_mask:0xf
	s_nop 1
	s_waitcnt lgkmcnt(0)
	v_add_f32_dpp v71, v71, v71 quad_perm:[2,3,0,1] row_mask:0xf bank_mask:0xf
	s_nop 1
	s_waitcnt lgkmcnt(0)
	v_add_f32_dpp v71, v71, v71 row_half_mirror row_mask:0xf bank_mask:0xf
	v_cndmask_b32_e64 v175, v229, v71, s[50:51]
	s_nop 1
	s_waitcnt lgkmcnt(0)
	v_add_f32_dpp v70, v70, v70 quad_perm:[1,0,3,2] row_mask:0xf bank_mask:0xf
	s_nop 1
	s_waitcnt lgkmcnt(0)
	v_add_f32_dpp v70, v70, v70 quad_perm:[2,3,0,1] row_mask:0xf bank_mask:0xf
	s_nop 1
	s_waitcnt lgkmcnt(0)
	v_add_f32_dpp v70, v70, v70 row_half_mirror row_mask:0xf bank_mask:0xf
	v_cndmask_b32_e64 v174, v230, v70, s[50:51]
	ds_read_b128 v[70:73], v49 offset:16560
	ds_read2st64_b32 v[138:139], v201 offset0:12 offset1:13
	s_waitcnt lgkmcnt(1)
	v_mov_b32_e32 v166, v73
	s_waitcnt lgkmcnt(0)
	v_mul_f32_e32 v140, v66, v138
	v_mul_f32_e32 v138, v67, v139
	ds_read2st64_b32 v[66:67], v201 offset0:14 offset1:15
	ds_read_b128 v[150:153], v215 offset:9728
	ds_read_b128 v[154:157], v215 offset:13824
	ds_read_b128 v[162:165], v215 offset:9856
	ds_read_b128 v[168:171], v215 offset:13952
	s_waitcnt lgkmcnt(3)
	v_pk_mul_f32 v[158:159], v[140:141], v[152:153] op_sel_hi:[0,1]
	v_pk_mul_f32 v[160:161], v[140:141], v[150:151] op_sel_hi:[0,1]
	v_pk_fma_f32 v[122:123], v[122:123], v[70:71], v[158:159] op_sel_hi:[1,0,1]
	v_pk_fma_f32 v[124:125], v[124:125], v[70:71], v[160:161] op_sel_hi:[1,0,1]
	v_mul_f32_e32 v68, v68, v66
	v_mul_f32_e32 v66, v69, v67
	s_waitcnt lgkmcnt(2)
	v_mul_f32_e32 v67, v155, v125
	v_mul_f32_e32 v69, v157, v123
	v_pk_mul_f32 v[158:159], v[152:153], v[138:139] op_sel_hi:[1,0]
	v_pk_mul_f32 v[160:161], v[150:151], v[138:139] op_sel_hi:[1,0]
	v_fmac_f32_e32 v67, v154, v124
	v_fmac_f32_e32 v69, v156, v122
	v_pk_fma_f32 v[126:127], v[126:127], v[70:71], v[158:159] op_sel:[0,1,0]
	v_pk_fma_f32 v[128:129], v[128:129], v[70:71], v[160:161] op_sel:[0,1,0]
	v_add_f32_e32 v67, v67, v69
	v_mul_f32_e32 v69, v155, v129
	v_mul_f32_e32 v139, v157, v127
	v_fmac_f32_e32 v69, v154, v128
	v_fmac_f32_e32 v139, v156, v126
	v_add_f32_e32 v69, v69, v139
	v_add_f32_e32 v69, 0, v69
	v_pk_mul_f32 v[158:159], v[152:153], v[68:69] op_sel_hi:[1,0]
	v_pk_mul_f32 v[160:161], v[150:151], v[68:69] op_sel_hi:[1,0]
	v_add_f32_e32 v67, 0, v67
	v_pk_fma_f32 v[130:131], v[130:131], v[72:73], v[158:159] op_sel_hi:[1,0,1]
	v_pk_fma_f32 v[132:133], v[132:133], v[72:73], v[160:161] op_sel_hi:[1,0,1]
	v_mul_f32_e32 v141, v157, v131
	v_mul_f32_e32 v139, v155, v133
	v_pk_mul_f32 v[152:153], v[152:153], v[66:67] op_sel_hi:[1,0]
	v_fmac_f32_e32 v139, v154, v132
	v_fmac_f32_e32 v141, v156, v130
	v_pk_fma_f32 v[134:135], v[134:135], v[166:167], v[152:153] op_sel_hi:[1,0,1]
	v_add_f32_e32 v139, v139, v141
	v_mul_f32_e32 v141, v157, v135
	v_pk_mul_f32 v[150:151], v[150:151], v[66:67] op_sel_hi:[1,0]
	v_fmac_f32_e32 v141, v156, v134
	v_pk_fma_f32 v[136:137], v[136:137], v[166:167], v[150:151] op_sel_hi:[1,0,1]
	s_waitcnt lgkmcnt(1)
	v_pk_mul_f32 v[150:151], v[140:141], v[164:165] op_sel_hi:[0,1]
	v_pk_mul_f32 v[152:153], v[140:141], v[162:163] op_sel_hi:[0,1]
	v_pk_fma_f32 v[150:151], v[118:119], v[70:71], v[150:151] op_sel_hi:[1,0,1]
	v_pk_fma_f32 v[152:153], v[120:121], v[70:71], v[152:153] op_sel_hi:[1,0,1]
	s_waitcnt lgkmcnt(0)
	v_mul_f32_e32 v119, v171, v151
	v_mul_f32_e32 v118, v169, v153
	v_fmac_f32_e32 v118, v168, v152
	v_fmac_f32_e32 v119, v170, v150
	v_add_f32_e32 v139, 0, v139
	v_add_f32_e32 v118, v118, v119
	v_mul_f32_e32 v73, v155, v137
	v_add_f32_e32 v67, v67, v118
	v_pk_mul_f32 v[118:119], v[138:139], v[164:165] op_sel_hi:[0,1]
	v_pk_mul_f32 v[120:121], v[138:139], v[162:163] op_sel_hi:[0,1]
	v_fmac_f32_e32 v73, v154, v136
	v_pk_fma_f32 v[154:155], v[114:115], v[70:71], v[118:119] op_sel:[0,1,0]
	v_pk_fma_f32 v[156:157], v[116:117], v[70:71], v[120:121] op_sel:[0,1,0]
	v_mul_f32_e32 v115, v171, v155
	v_mul_f32_e32 v114, v169, v157
	v_fmac_f32_e32 v114, v168, v156
	v_fmac_f32_e32 v115, v170, v154
	v_add_f32_e32 v114, v114, v115
	v_add_f32_e32 v73, v73, v141
	v_add_f32_e32 v69, v69, v114
	v_add_f32_e32 v73, 0, v73
	v_pk_mul_f32 v[114:115], v[68:69], v[164:165] op_sel_hi:[0,1]
	v_pk_mul_f32 v[116:117], v[68:69], v[162:163] op_sel_hi:[0,1]
	v_pk_fma_f32 v[158:159], v[110:111], v[72:73], v[114:115] op_sel_hi:[1,0,1]
	v_pk_fma_f32 v[160:161], v[112:113], v[72:73], v[116:117] op_sel_hi:[1,0,1]
	v_mul_f32_e32 v111, v171, v159
	v_mul_f32_e32 v110, v169, v161
	v_fmac_f32_e32 v110, v168, v160
	v_fmac_f32_e32 v111, v170, v158
	v_add_f32_e32 v110, v110, v111
	v_add_f32_e32 v118, v139, v110
	v_pk_mul_f32 v[110:111], v[164:165], v[66:67] op_sel_hi:[1,0]
	v_pk_mul_f32 v[112:113], v[162:163], v[66:67] op_sel_hi:[1,0]
	v_pk_fma_f32 v[162:163], v[106:107], v[166:167], v[110:111] op_sel_hi:[1,0,1]
	v_pk_fma_f32 v[164:165], v[108:109], v[166:167], v[112:113] op_sel_hi:[1,0,1]
	v_mul_f32_e32 v107, v171, v163
	v_mul_f32_e32 v106, v169, v165
	v_fmac_f32_e32 v106, v168, v164
	v_fmac_f32_e32 v107, v170, v162
	v_add_f32_e32 v106, v106, v107
	v_add_f32_e32 v73, v106, v73
	ds_read_b128 v[106:109], v215 offset:9984
	ds_read_b128 v[110:113], v215 offset:14080
	s_waitcnt lgkmcnt(1)
	v_pk_mul_f32 v[114:115], v[140:141], v[108:109] op_sel_hi:[0,1]
	v_pk_mul_f32 v[116:117], v[140:141], v[106:107] op_sel_hi:[0,1]
	v_pk_fma_f32 v[90:91], v[90:91], v[70:71], v[114:115] op_sel_hi:[1,0,1]
	v_pk_fma_f32 v[92:93], v[92:93], v[70:71], v[116:117] op_sel_hi:[1,0,1]
	s_waitcnt lgkmcnt(0)
	v_mul_f32_e32 v115, v113, v91
	v_mul_f32_e32 v114, v111, v93
	v_fmac_f32_e32 v114, v110, v92
	v_fmac_f32_e32 v115, v112, v90
	v_add_f32_e32 v114, v114, v115
	v_add_f32_e32 v67, v67, v114
	v_pk_mul_f32 v[114:115], v[138:139], v[108:109] op_sel_hi:[0,1]
	v_pk_mul_f32 v[116:117], v[138:139], v[106:107] op_sel_hi:[0,1]
	v_pk_fma_f32 v[94:95], v[94:95], v[70:71], v[114:115] op_sel:[0,1,0]
	v_pk_fma_f32 v[96:97], v[96:97], v[70:71], v[116:117] op_sel:[0,1,0]
	v_mul_f32_e32 v115, v113, v95
	v_mul_f32_e32 v114, v111, v97
	v_fmac_f32_e32 v114, v110, v96
	v_fmac_f32_e32 v115, v112, v94
	v_add_f32_e32 v114, v114, v115
	v_add_f32_e32 v69, v69, v114
	v_pk_mul_f32 v[114:115], v[68:69], v[108:109] op_sel_hi:[0,1]
	v_pk_mul_f32 v[116:117], v[68:69], v[106:107] op_sel_hi:[0,1]
	v_pk_mul_f32 v[108:109], v[66:67], v[108:109] op_sel_hi:[0,1]
	v_pk_mul_f32 v[106:107], v[66:67], v[106:107] op_sel_hi:[0,1]
	v_pk_fma_f32 v[168:169], v[102:103], v[166:167], v[108:109] op_sel_hi:[1,0,1]
	v_pk_fma_f32 v[170:171], v[104:105], v[166:167], v[106:107] op_sel_hi:[1,0,1]
	v_pk_fma_f32 v[98:99], v[98:99], v[72:73], v[114:115] op_sel_hi:[1,0,1]
	v_pk_fma_f32 v[100:101], v[100:101], v[72:73], v[116:117] op_sel_hi:[1,0,1]
	v_mul_f32_e32 v102, v111, v171
	v_mul_f32_e32 v103, v113, v169
	v_mul_f32_e32 v114, v111, v101
	v_mul_f32_e32 v115, v113, v99
	v_fmac_f32_e32 v102, v110, v170
	v_fmac_f32_e32 v103, v112, v168
	v_fmac_f32_e32 v114, v110, v100
	v_fmac_f32_e32 v115, v112, v98
	v_add_f32_e32 v102, v102, v103
	v_add_f32_e32 v114, v114, v115
	v_add_f32_e32 v115, v73, v102
	ds_read_b128 v[102:105], v215 offset:10112
	ds_read_b128 v[106:109], v215 offset:14208
	v_add_f32_e32 v114, v118, v114
	s_waitcnt lgkmcnt(1)
	v_pk_mul_f32 v[110:111], v[140:141], v[104:105] op_sel_hi:[0,1]
	v_pk_mul_f32 v[112:113], v[140:141], v[102:103] op_sel_hi:[0,1]
	v_pk_fma_f32 v[140:141], v[86:87], v[70:71], v[110:111] op_sel_hi:[1,0,1]
	v_pk_fma_f32 v[172:173], v[88:89], v[70:71], v[112:113] op_sel_hi:[1,0,1]
	s_waitcnt lgkmcnt(0)
	v_mul_f32_e32 v86, v109, v141
	v_mul_f32_e32 v73, v107, v173
	v_fmac_f32_e32 v73, v106, v172
	v_fmac_f32_e32 v86, v108, v140
	v_add_f32_e32 v73, v73, v86
	v_pk_mul_f32 v[86:87], v[138:139], v[104:105] op_sel_hi:[0,1]
	v_pk_mul_f32 v[88:89], v[138:139], v[102:103] op_sel_hi:[0,1]
	v_pk_fma_f32 v[138:139], v[82:83], v[70:71], v[86:87] op_sel:[0,1,0]
	v_pk_fma_f32 v[70:71], v[84:85], v[70:71], v[88:89] op_sel:[0,1,0]
	v_add_f32_e32 v110, v67, v73
	v_mul_f32_e32 v67, v107, v71
	v_mul_f32_e32 v73, v109, v139
	v_fmac_f32_e32 v67, v106, v70
	v_fmac_f32_e32 v73, v108, v138
	v_add_f32_e32 v67, v67, v73
	v_pk_mul_f32 v[82:83], v[68:69], v[104:105] op_sel_hi:[0,1]
	v_pk_mul_f32 v[84:85], v[68:69], v[102:103] op_sel_hi:[0,1]
	v_add_f32_e32 v86, v69, v67
	v_pk_fma_f32 v[68:69], v[78:79], v[72:73], v[82:83] op_sel_hi:[1,0,1]
	v_pk_fma_f32 v[72:73], v[80:81], v[72:73], v[84:85] op_sel_hi:[1,0,1]
	v_mul_f32_e32 v78, v109, v69
	v_mul_f32_e32 v67, v107, v73
	v_fmac_f32_e32 v67, v106, v72
	v_fmac_f32_e32 v78, v108, v68
	v_add_f32_e32 v67, v67, v78
	v_pk_mul_f32 v[78:79], v[66:67], v[104:105] op_sel_hi:[0,1]
	v_pk_mul_f32 v[80:81], v[66:67], v[102:103] op_sel_hi:[0,1]
	v_add_f32_e32 v82, v114, v67
	v_pk_fma_f32 v[66:67], v[74:75], v[166:167], v[78:79] op_sel_hi:[1,0,1]
	v_pk_fma_f32 v[166:167], v[76:77], v[166:167], v[80:81] op_sel_hi:[1,0,1]
	v_mul_f32_e32 v75, v109, v67
	v_mul_f32_e32 v74, v107, v167
	v_fmac_f32_e32 v74, v106, v166
	v_fmac_f32_e32 v75, v108, v66
	v_add_f32_e32 v74, v74, v75
	s_nop 1
	v_add_f32_e32 v74, v115, v74
	s_waitcnt lgkmcnt(0)
	v_add_f32_dpp v75, v110, v110 quad_perm:[1,0,3,2] row_mask:0xf bank_mask:0xf
	s_nop 1
	s_waitcnt lgkmcnt(0)
	v_add_f32_dpp v75, v75, v75 quad_perm:[2,3,0,1] row_mask:0xf bank_mask:0xf
	s_nop 1
	s_waitcnt lgkmcnt(0)
	v_add_f32_dpp v75, v75, v75 row_half_mirror row_mask:0xf bank_mask:0xf
	v_cndmask_b32_e64 v179, v177, v75, s[52:53]
	s_nop 1
	s_waitcnt lgkmcnt(0)
	v_add_f32_dpp v75, v86, v86 quad_perm:[1,0,3,2] row_mask:0xf bank_mask:0xf
	s_nop 1
	s_waitcnt lgkmcnt(0)
	v_add_f32_dpp v75, v75, v75 quad_perm:[2,3,0,1] row_mask:0xf bank_mask:0xf
	s_nop 1
	s_waitcnt lgkmcnt(0)
	v_add_f32_dpp v75, v75, v75 row_half_mirror row_mask:0xf bank_mask:0xf
	v_cndmask_b32_e64 v181, v176, v75, s[52:53]
	s_nop 1
	s_waitcnt lgkmcnt(0)
	v_add_f32_dpp v75, v82, v82 quad_perm:[1,0,3,2] row_mask:0xf bank_mask:0xf
	s_nop 1
	s_waitcnt lgkmcnt(0)
	v_add_f32_dpp v75, v75, v75 quad_perm:[2,3,0,1] row_mask:0xf bank_mask:0xf
	s_nop 1
	s_waitcnt lgkmcnt(0)
	v_add_f32_dpp v75, v75, v75 row_half_mirror row_mask:0xf bank_mask:0xf
	v_cndmask_b32_e64 v183, v175, v75, s[52:53]
	s_nop 1
	s_waitcnt lgkmcnt(0)
	v_add_f32_dpp v74, v74, v74 quad_perm:[1,0,3,2] row_mask:0xf bank_mask:0xf
	s_nop 1
	s_waitcnt lgkmcnt(0)
	v_add_f32_dpp v74, v74, v74 quad_perm:[2,3,0,1] row_mask:0xf bank_mask:0xf
	s_nop 1
	s_waitcnt lgkmcnt(0)
	v_add_f32_dpp v74, v74, v74 row_half_mirror row_mask:0xf bank_mask:0xf
	v_cndmask_b32_e64 v185, v174, v74, s[52:53]
	ds_read_b128 v[74:77], v49 offset:16448
	ds_read_b128 v[174:177], v49 offset:16576
	ds_read2st64_b32 v[78:79], v201 offset0:16 offset1:17
	s_waitcnt lgkmcnt(1)
	v_mov_b32_e32 v184, v177
	s_waitcnt lgkmcnt(0)
	v_mul_f32_e32 v82, v74, v78
	v_mul_f32_e32 v178, v75, v79
	ds_read2st64_b32 v[74:75], v201 offset0:18 offset1:19
	s_waitcnt lgkmcnt(0)
	v_mul_f32_e32 v180, v76, v74
	v_mul_f32_e32 v182, v77, v75
	ds_read_b128 v[74:77], v215 offset:10240
	ds_read_b128 v[78:81], v215 offset:14336
	s_waitcnt lgkmcnt(1)
	v_pk_mul_f32 v[84:85], v[82:83], v[76:77] op_sel_hi:[0,1]
	v_pk_mul_f32 v[86:87], v[82:83], v[74:75] op_sel_hi:[0,1]
	v_pk_fma_f32 v[118:119], v[122:123], v[174:175], v[84:85] op_sel_hi:[1,0,1]
	v_pk_fma_f32 v[120:121], v[124:125], v[174:175], v[86:87] op_sel_hi:[1,0,1]
	s_waitcnt lgkmcnt(0)
	v_mul_f32_e32 v84, v81, v119
	v_mul_f32_e32 v83, v79, v121
	v_fmac_f32_e32 v83, v78, v120
	v_fmac_f32_e32 v84, v80, v118
	v_add_f32_e32 v83, v83, v84
	v_pk_mul_f32 v[84:85], v[76:77], v[178:179] op_sel_hi:[1,0]
	v_pk_mul_f32 v[86:87], v[74:75], v[178:179] op_sel_hi:[1,0]
	v_pk_fma_f32 v[122:123], v[126:127], v[174:175], v[84:85] op_sel:[0,1,0]
	v_pk_fma_f32 v[124:125], v[128:129], v[174:175], v[86:87] op_sel:[0,1,0]
	v_mul_f32_e32 v85, v81, v123
	v_mul_f32_e32 v84, v79, v125
	v_fmac_f32_e32 v84, v78, v124
	v_fmac_f32_e32 v85, v80, v122
	v_add_f32_e32 v84, v84, v85
	v_add_f32_e32 v88, 0, v84
	v_pk_mul_f32 v[84:85], v[76:77], v[180:181] op_sel_hi:[1,0]
	v_pk_mul_f32 v[86:87], v[74:75], v[180:181] op_sel_hi:[1,0]
	v_pk_mul_f32 v[76:77], v[76:77], v[182:183] op_sel_hi:[1,0]
	v_pk_mul_f32 v[74:75], v[74:75], v[182:183] op_sel_hi:[1,0]
	v_pk_fma_f32 v[126:127], v[130:131], v[176:177], v[84:85] op_sel_hi:[1,0,1]
	v_pk_fma_f32 v[128:129], v[132:133], v[176:177], v[86:87] op_sel_hi:[1,0,1]
	v_pk_fma_f32 v[130:131], v[134:135], v[184:185], v[76:77] op_sel_hi:[1,0,1]
	v_pk_fma_f32 v[132:133], v[136:137], v[184:185], v[74:75] op_sel_hi:[1,0,1]
	v_mul_f32_e32 v75, v81, v131
	v_mul_f32_e32 v74, v79, v133
	v_fmac_f32_e32 v74, v78, v132
	v_fmac_f32_e32 v75, v80, v130
	v_mul_f32_e32 v84, v79, v129
	v_mul_f32_e32 v85, v81, v127
	v_add_f32_e32 v74, v74, v75
	v_fmac_f32_e32 v84, v78, v128
	v_fmac_f32_e32 v85, v80, v126
	v_add_f32_e32 v134, 0, v74
	ds_read_b128 v[74:77], v215 offset:10368
	ds_read_b128 v[78:81], v215 offset:14464
	v_add_f32_e32 v83, 0, v83
	v_add_f32_e32 v84, v84, v85
	v_add_f32_e32 v89, 0, v84
	s_waitcnt lgkmcnt(1)
	v_pk_mul_f32 v[84:85], v[82:83], v[76:77] op_sel_hi:[0,1]
	v_pk_mul_f32 v[86:87], v[82:83], v[74:75] op_sel_hi:[0,1]
	v_pk_fma_f32 v[114:115], v[150:151], v[174:175], v[84:85] op_sel_hi:[1,0,1]
	v_pk_fma_f32 v[116:117], v[152:153], v[174:175], v[86:87] op_sel_hi:[1,0,1]
	s_waitcnt lgkmcnt(0)
	v_mul_f32_e32 v85, v81, v115
	v_mul_f32_e32 v84, v79, v117
	v_fmac_f32_e32 v84, v78, v116
	v_fmac_f32_e32 v85, v80, v114
	v_add_f32_e32 v84, v84, v85
	v_add_f32_e32 v83, v83, v84
	v_pk_mul_f32 v[84:85], v[178:179], v[76:77] op_sel_hi:[0,1]
	v_pk_mul_f32 v[86:87], v[178:179], v[74:75] op_sel_hi:[0,1]
	v_pk_fma_f32 v[110:111], v[154:155], v[174:175], v[84:85] op_sel:[0,1,0]
	v_pk_fma_f32 v[112:113], v[156:157], v[174:175], v[86:87] op_sel:[0,1,0]
	v_mul_f32_e32 v85, v81, v111
	v_mul_f32_e32 v84, v79, v113
	v_fmac_f32_e32 v84, v78, v112
	v_fmac_f32_e32 v85, v80, v110
	v_add_f32_e32 v84, v84, v85
	v_add_f32_e32 v135, v88, v84
	v_pk_mul_f32 v[84:85], v[180:181], v[76:77] op_sel_hi:[0,1]
	v_pk_mul_f32 v[86:87], v[180:181], v[74:75] op_sel_hi:[0,1]
	v_pk_mul_f32 v[76:77], v[76:77], v[182:183] op_sel_hi:[1,0]
	v_pk_mul_f32 v[74:75], v[74:75], v[182:183] op_sel_hi:[1,0]
	v_pk_fma_f32 v[102:103], v[162:163], v[184:185], v[76:77] op_sel_hi:[1,0,1]
	v_pk_fma_f32 v[104:105], v[164:165], v[184:185], v[74:75] op_sel_hi:[1,0,1]
	v_mul_f32_e32 v75, v81, v103
	v_mul_f32_e32 v74, v79, v105
	v_pk_fma_f32 v[106:107], v[158:159], v[176:177], v[84:85] op_sel_hi:[1,0,1]
	v_pk_fma_f32 v[108:109], v[160:161], v[176:177], v[86:87] op_sel_hi:[1,0,1]
	v_fmac_f32_e32 v74, v78, v104
	v_fmac_f32_e32 v75, v80, v102
	v_mul_f32_e32 v84, v79, v109
	v_mul_f32_e32 v85, v81, v107
	v_add_f32_e32 v74, v74, v75
	v_fmac_f32_e32 v84, v78, v108
	v_fmac_f32_e32 v85, v80, v106
	v_add_f32_e32 v134, v74, v134
	ds_read_b128 v[74:77], v215 offset:10496
	ds_read_b128 v[78:81], v215 offset:14592
	v_add_f32_e32 v84, v84, v85
	v_add_f32_e32 v136, v89, v84
	s_waitcnt lgkmcnt(1)
	v_pk_mul_f32 v[84:85], v[82:83], v[76:77] op_sel_hi:[0,1]
	v_pk_mul_f32 v[88:89], v[82:83], v[74:75] op_sel_hi:[0,1]
	v_pk_fma_f32 v[86:87], v[90:91], v[174:175], v[84:85] op_sel_hi:[1,0,1]
	v_pk_fma_f32 v[88:89], v[92:93], v[174:175], v[88:89] op_sel_hi:[1,0,1]
	s_waitcnt lgkmcnt(0)
	v_mul_f32_e32 v85, v81, v87
	v_mul_f32_e32 v84, v79, v89
	v_fmac_f32_e32 v84, v78, v88
	v_fmac_f32_e32 v85, v80, v86
	v_add_f32_e32 v84, v84, v85
	v_add_f32_e32 v154, v83, v84
	v_pk_mul_f32 v[84:85], v[178:179], v[76:77] op_sel_hi:[0,1]
	v_pk_mul_f32 v[92:93], v[178:179], v[74:75] op_sel_hi:[0,1]
	v_pk_fma_f32 v[90:91], v[94:95], v[174:175], v[84:85] op_sel:[0,1,0]
	v_pk_fma_f32 v[92:93], v[96:97], v[174:175], v[92:93] op_sel:[0,1,0]
	v_mul_f32_e32 v84, v81, v91
	v_mul_f32_e32 v83, v79, v93
	v_fmac_f32_e32 v83, v78, v92
	v_fmac_f32_e32 v84, v80, v90
	v_add_f32_e32 v83, v83, v84
	v_pk_mul_f32 v[84:85], v[180:181], v[76:77] op_sel_hi:[0,1]
	v_pk_mul_f32 v[96:97], v[180:181], v[74:75] op_sel_hi:[0,1]
	v_pk_mul_f32 v[76:77], v[182:183], v[76:77] op_sel_hi:[0,1]
	v_pk_mul_f32 v[74:75], v[182:183], v[74:75] op_sel_hi:[0,1]
	v_pk_fma_f32 v[94:95], v[98:99], v[176:177], v[84:85] op_sel_hi:[1,0,1]
	v_pk_fma_f32 v[96:97], v[100:101], v[176:177], v[96:97] op_sel_hi:[1,0,1]
	v_pk_fma_f32 v[98:99], v[168:169], v[184:185], v[76:77] op_sel_hi:[1,0,1]
	v_pk_fma_f32 v[100:101], v[170:171], v[184:185], v[74:75] op_sel_hi:[1,0,1]
	v_add_f32_e32 v155, v135, v83
	v_mul_f32_e32 v83, v79, v97
	v_mul_f32_e32 v84, v81, v95
	v_mul_f32_e32 v74, v79, v101
	v_mul_f32_e32 v75, v81, v99
	v_fmac_f32_e32 v83, v78, v96
	v_fmac_f32_e32 v84, v80, v94
	v_fmac_f32_e32 v74, v78, v100
	v_fmac_f32_e32 v75, v80, v98
	v_add_f32_e32 v83, v83, v84
	v_add_f32_e32 v74, v74, v75
	v_add_f32_e32 v156, v136, v83
	v_add_f32_e32 v157, v134, v74
	ds_read_b128 v[134:137], v215 offset:10624
	ds_read_b128 v[150:153], v215 offset:14720
	s_waitcnt lgkmcnt(1)
	v_pk_mul_f32 v[74:75], v[82:83], v[136:137] op_sel_hi:[0,1]
	v_pk_mul_f32 v[76:77], v[82:83], v[134:135] op_sel_hi:[0,1]
	v_pk_fma_f32 v[82:83], v[140:141], v[174:175], v[74:75] op_sel_hi:[1,0,1]
	v_pk_fma_f32 v[84:85], v[172:173], v[174:175], v[76:77] op_sel_hi:[1,0,1]
	s_waitcnt lgkmcnt(0)
	v_mul_f32_e32 v75, v153, v83
	v_mul_f32_e32 v74, v151, v85
	v_fmac_f32_e32 v74, v150, v84
	v_fmac_f32_e32 v75, v152, v82
	v_add_f32_e32 v74, v74, v75
	v_add_f32_e32 v140, v154, v74
	v_pk_mul_f32 v[74:75], v[178:179], v[136:137] op_sel_hi:[0,1]
	v_pk_mul_f32 v[76:77], v[178:179], v[134:135] op_sel_hi:[0,1]
	v_pk_fma_f32 v[78:79], v[138:139], v[174:175], v[74:75] op_sel:[0,1,0]
	v_pk_fma_f32 v[80:81], v[70:71], v[174:175], v[76:77] op_sel:[0,1,0]
	v_mul_f32_e32 v71, v153, v79
	v_mul_f32_e32 v70, v151, v81
	v_fmac_f32_e32 v70, v150, v80
	v_fmac_f32_e32 v71, v152, v78
	v_add_f32_e32 v70, v70, v71
	v_add_f32_e32 v138, v155, v70
	v_pk_mul_f32 v[70:71], v[180:181], v[136:137] op_sel_hi:[0,1]
	v_pk_mul_f32 v[76:77], v[180:181], v[134:135] op_sel_hi:[0,1]
	v_pk_fma_f32 v[74:75], v[68:69], v[176:177], v[70:71] op_sel_hi:[1,0,1]
	v_pk_fma_f32 v[76:77], v[72:73], v[176:177], v[76:77] op_sel_hi:[1,0,1]
	v_mul_f32_e32 v69, v153, v75
	v_mul_f32_e32 v68, v151, v77
	v_fmac_f32_e32 v68, v150, v76
	v_fmac_f32_e32 v69, v152, v74
	v_add_f32_e32 v68, v68, v69
	v_add_f32_e32 v154, v156, v68
	v_pk_mul_f32 v[68:69], v[182:183], v[136:137] op_sel_hi:[0,1]
	v_pk_mul_f32 v[72:73], v[182:183], v[134:135] op_sel_hi:[0,1]
	v_pk_fma_f32 v[70:71], v[66:67], v[184:185], v[68:69] op_sel_hi:[1,0,1]
	v_pk_fma_f32 v[72:73], v[166:167], v[184:185], v[72:73] op_sel_hi:[1,0,1]
	v_mul_f32_e32 v67, v153, v71
	v_mul_f32_e32 v66, v151, v73
	v_fmac_f32_e32 v66, v150, v72
	v_fmac_f32_e32 v67, v152, v70
	v_add_f32_e32 v66, v66, v67
	s_nop 1
	v_add_f32_e32 v66, v157, v66
	s_waitcnt lgkmcnt(0)
	v_add_f32_dpp v67, v140, v140 quad_perm:[1,0,3,2] row_mask:0xf bank_mask:0xf
	s_nop 1
	s_waitcnt lgkmcnt(0)
	v_add_f32_dpp v67, v67, v67 quad_perm:[2,3,0,1] row_mask:0xf bank_mask:0xf
	s_nop 1
	s_waitcnt lgkmcnt(0)
	v_add_f32_dpp v67, v67, v67 row_half_mirror row_mask:0xf bank_mask:0xf
	v_cndmask_b32_e64 v141, v179, v67, s[54:55]
	s_nop 1
	s_waitcnt lgkmcnt(0)
	v_add_f32_dpp v67, v138, v138 quad_perm:[1,0,3,2] row_mask:0xf bank_mask:0xf
	s_nop 1
	s_waitcnt lgkmcnt(0)
	v_add_f32_dpp v67, v67, v67 quad_perm:[2,3,0,1] row_mask:0xf bank_mask:0xf
	s_nop 1
	s_waitcnt lgkmcnt(0)
	v_add_f32_dpp v67, v67, v67 row_half_mirror row_mask:0xf bank_mask:0xf
	v_cndmask_b32_e64 v139, v181, v67, s[54:55]
	s_nop 1
	s_waitcnt lgkmcnt(0)
	v_add_f32_dpp v67, v154, v154 quad_perm:[1,0,3,2] row_mask:0xf bank_mask:0xf
	s_nop 1
	s_waitcnt lgkmcnt(0)
	v_add_f32_dpp v67, v67, v67 quad_perm:[2,3,0,1] row_mask:0xf bank_mask:0xf
	s_nop 1
	s_waitcnt lgkmcnt(0)
	v_add_f32_dpp v67, v67, v67 row_half_mirror row_mask:0xf bank_mask:0xf
	v_cndmask_b32_e64 v137, v183, v67, s[54:55]
	s_nop 1
	s_waitcnt lgkmcnt(0)
	v_add_f32_dpp v66, v66, v66 quad_perm:[1,0,3,2] row_mask:0xf bank_mask:0xf
	s_nop 1
	s_waitcnt lgkmcnt(0)
	v_add_f32_dpp v66, v66, v66 quad_perm:[2,3,0,1] row_mask:0xf bank_mask:0xf
	s_nop 1
	s_waitcnt lgkmcnt(0)
	v_add_f32_dpp v66, v66, v66 row_half_mirror row_mask:0xf bank_mask:0xf
	v_cndmask_b32_e64 v135, v185, v66, s[54:55]
	ds_read_b128 v[150:153], v49 offset:16464
	ds_read_b128 v[66:69], v49 offset:16592
	ds_read2st64_b32 v[154:155], v201 offset0:20 offset1:21
	s_waitcnt lgkmcnt(0)
	v_mul_f32_e32 v140, v150, v154
	v_mul_f32_e32 v136, v151, v155
	ds_read2st64_b32 v[150:151], v201 offset0:22 offset1:23
	s_waitcnt lgkmcnt(0)
	v_mul_f32_e32 v138, v152, v150
	v_mul_f32_e32 v134, v153, v151
	ds_read_b128 v[150:153], v215 offset:10752
	ds_read_b128 v[154:157], v215 offset:14848
	s_waitcnt lgkmcnt(1)
	v_pk_mul_f32 v[158:159], v[140:141], v[152:153] op_sel_hi:[0,1]
	v_pk_mul_f32 v[160:161], v[140:141], v[150:151] op_sel_hi:[0,1]
	v_pk_fma_f32 v[118:119], v[118:119], v[66:67], v[158:159] op_sel_hi:[1,0,1]
	v_pk_fma_f32 v[120:121], v[120:121], v[66:67], v[160:161] op_sel_hi:[1,0,1]
	s_waitcnt lgkmcnt(0)
	v_mul_f32_e32 v159, v157, v119
	v_mul_f32_e32 v158, v155, v121
	v_fmac_f32_e32 v158, v154, v120
	v_fmac_f32_e32 v159, v156, v118
	v_add_f32_e32 v158, v158, v159
	v_add_f32_e32 v164, 0, v158
	v_pk_mul_f32 v[158:159], v[152:153], v[136:137] op_sel_hi:[1,0]
	v_pk_mul_f32 v[160:161], v[150:151], v[136:137] op_sel_hi:[1,0]
	v_pk_fma_f32 v[122:123], v[122:123], v[66:67], v[158:159] op_sel:[0,1,0]
	v_pk_fma_f32 v[124:125], v[124:125], v[66:67], v[160:161] op_sel:[0,1,0]
	v_mul_f32_e32 v159, v157, v123
	v_mul_f32_e32 v158, v155, v125
	v_fmac_f32_e32 v158, v154, v124
	v_fmac_f32_e32 v159, v156, v122
	v_add_f32_e32 v158, v158, v159
	v_add_f32_e32 v165, 0, v158
	v_pk_mul_f32 v[158:159], v[152:153], v[138:139] op_sel_hi:[1,0]
	v_pk_mul_f32 v[160:161], v[150:151], v[138:139] op_sel_hi:[1,0]
	v_pk_fma_f32 v[126:127], v[126:127], v[68:69], v[158:159] op_sel_hi:[1,0,1]
	v_pk_fma_f32 v[128:129], v[128:129], v[68:69], v[160:161] op_sel_hi:[1,0,1]
	v_mul_f32_e32 v159, v157, v127
	v_mul_f32_e32 v158, v155, v129
	v_fmac_f32_e32 v158, v154, v128
	v_fmac_f32_e32 v159, v156, v126
	v_add_f32_e32 v158, v158, v159
	v_add_f32_e32 v166, 0, v158
	v_pk_mul_f32 v[152:153], v[152:153], v[134:135] op_sel_hi:[1,0]
	v_pk_mul_f32 v[158:159], v[150:151], v[134:135] op_sel_hi:[1,0]
	v_mov_b32_e32 v150, v69
	v_pk_fma_f32 v[130:131], v[130:131], v[150:151], v[152:153] op_sel_hi:[1,0,1]
	v_pk_fma_f32 v[132:133], v[132:133], v[150:151], v[158:159] op_sel_hi:[1,0,1]
	v_mul_f32_e32 v151, v157, v131
	v_mul_f32_e32 v69, v155, v133
	v_fmac_f32_e32 v69, v154, v132
	v_fmac_f32_e32 v151, v156, v130
	ds_read_b128 v[152:155], v215 offset:10880
	ds_read_b128 v[156:159], v215 offset:14976
	v_add_f32_e32 v69, v69, v151
	v_add_f32_e32 v69, 0, v69
	s_waitcnt lgkmcnt(1)
	v_pk_mul_f32 v[160:161], v[140:141], v[154:155] op_sel_hi:[0,1]
	v_pk_mul_f32 v[162:163], v[140:141], v[152:153] op_sel_hi:[0,1]
	v_pk_fma_f32 v[114:115], v[114:115], v[66:67], v[160:161] op_sel_hi:[1,0,1]
	v_pk_fma_f32 v[116:117], v[116:117], v[66:67], v[162:163] op_sel_hi:[1,0,1]
	s_waitcnt lgkmcnt(0)
	v_mul_f32_e32 v160, v159, v115
	v_mul_f32_e32 v151, v157, v117
	v_fmac_f32_e32 v151, v156, v116
	v_fmac_f32_e32 v160, v158, v114
	v_add_f32_e32 v151, v151, v160
	v_pk_mul_f32 v[160:161], v[136:137], v[154:155] op_sel_hi:[0,1]
	v_pk_mul_f32 v[162:163], v[136:137], v[152:153] op_sel_hi:[0,1]
	v_pk_fma_f32 v[110:111], v[110:111], v[66:67], v[160:161] op_sel:[0,1,0]
	v_pk_fma_f32 v[112:113], v[112:113], v[66:67], v[162:163] op_sel:[0,1,0]
	v_mul_f32_e32 v161, v159, v111
	v_mul_f32_e32 v160, v157, v113
	v_fmac_f32_e32 v160, v156, v112
	v_fmac_f32_e32 v161, v158, v110
	v_add_f32_e32 v160, v160, v161
	v_add_f32_e32 v172, v165, v160
	v_pk_mul_f32 v[160:161], v[138:139], v[154:155] op_sel_hi:[0,1]
	v_pk_mul_f32 v[162:163], v[138:139], v[152:153] op_sel_hi:[0,1]
	v_pk_fma_f32 v[106:107], v[106:107], v[68:69], v[160:161] op_sel_hi:[1,0,1]
	v_pk_fma_f32 v[108:109], v[108:109], v[68:69], v[162:163] op_sel_hi:[1,0,1]
	v_mul_f32_e32 v161, v159, v107
	v_mul_f32_e32 v160, v157, v109
	v_fmac_f32_e32 v160, v156, v108
	v_fmac_f32_e32 v161, v158, v106
	v_add_f32_e32 v151, v164, v151
	v_add_f32_e32 v160, v160, v161
	v_pk_mul_f32 v[154:155], v[154:155], v[134:135] op_sel_hi:[1,0]
	v_pk_mul_f32 v[152:153], v[152:153], v[134:135] op_sel_hi:[1,0]
	v_add_f32_e32 v173, v166, v160
	v_pk_fma_f32 v[102:103], v[102:103], v[150:151], v[154:155] op_sel_hi:[1,0,1]
	v_pk_fma_f32 v[104:105], v[104:105], v[150:151], v[152:153] op_sel_hi:[1,0,1]
	ds_read_b128 v[164:167], v215 offset:11008
	ds_read_b128 v[168:171], v215 offset:15104
	v_mul_f32_e32 v152, v157, v105
	v_mul_f32_e32 v153, v159, v103
	v_fmac_f32_e32 v152, v156, v104
	v_fmac_f32_e32 v153, v158, v102
	v_add_f32_e32 v152, v152, v153
	v_add_f32_e32 v69, v152, v69
	s_waitcnt lgkmcnt(1)
	v_pk_mul_f32 v[152:153], v[140:141], v[166:167] op_sel_hi:[0,1]
	v_pk_mul_f32 v[154:155], v[140:141], v[164:165] op_sel_hi:[0,1]
	v_pk_fma_f32 v[152:153], v[86:87], v[66:67], v[152:153] op_sel_hi:[1,0,1]
	v_pk_fma_f32 v[154:155], v[88:89], v[66:67], v[154:155] op_sel_hi:[1,0,1]
	s_waitcnt lgkmcnt(0)
	v_mul_f32_e32 v87, v171, v153
	v_mul_f32_e32 v86, v169, v155
	v_fmac_f32_e32 v86, v168, v154
	v_fmac_f32_e32 v87, v170, v152
	v_add_f32_e32 v86, v86, v87
	v_add_f32_e32 v151, v151, v86
	v_pk_mul_f32 v[86:87], v[136:137], v[166:167] op_sel_hi:[0,1]
	v_pk_mul_f32 v[88:89], v[136:137], v[164:165] op_sel_hi:[0,1]
	v_pk_fma_f32 v[156:157], v[90:91], v[66:67], v[86:87] op_sel:[0,1,0]
	v_pk_fma_f32 v[158:159], v[92:93], v[66:67], v[88:89] op_sel:[0,1,0]
	v_mul_f32_e32 v87, v171, v157
	v_mul_f32_e32 v86, v169, v159
	v_fmac_f32_e32 v86, v168, v158
	v_fmac_f32_e32 v87, v170, v156
	v_add_f32_e32 v86, v86, v87
	v_add_f32_e32 v172, v172, v86
	v_pk_mul_f32 v[86:87], v[138:139], v[166:167] op_sel_hi:[0,1]
	v_pk_mul_f32 v[88:89], v[138:139], v[164:165] op_sel_hi:[0,1]
	v_pk_fma_f32 v[160:161], v[94:95], v[68:69], v[86:87] op_sel_hi:[1,0,1]
	v_pk_fma_f32 v[162:163], v[96:97], v[68:69], v[88:89] op_sel_hi:[1,0,1]
	v_mul_f32_e32 v87, v171, v161
	v_mul_f32_e32 v86, v169, v163
	v_fmac_f32_e32 v86, v168, v162
	v_fmac_f32_e32 v87, v170, v160
	v_add_f32_e32 v86, v86, v87
	v_add_f32_e32 v173, v173, v86
	v_pk_mul_f32 v[86:87], v[134:135], v[166:167] op_sel_hi:[0,1]
	v_pk_mul_f32 v[88:89], v[134:135], v[164:165] op_sel_hi:[0,1]
	v_pk_fma_f32 v[98:99], v[98:99], v[150:151], v[86:87] op_sel_hi:[1,0,1]
	v_pk_fma_f32 v[100:101], v[100:101], v[150:151], v[88:89] op_sel_hi:[1,0,1]
	v_mul_f32_e32 v87, v171, v99
	v_mul_f32_e32 v86, v169, v101
	v_fmac_f32_e32 v86, v168, v100
	v_fmac_f32_e32 v87, v170, v98
	v_add_f32_e32 v86, v86, v87
	v_add_f32_e32 v174, v69, v86
	ds_read_b128 v[86:89], v215 offset:11136
	ds_read_b128 v[90:93], v215 offset:15232
	s_waitcnt lgkmcnt(1)
	v_pk_mul_f32 v[94:95], v[140:141], v[88:89] op_sel_hi:[0,1]
	v_pk_mul_f32 v[96:97], v[140:141], v[86:87] op_sel_hi:[0,1]
	v_pk_fma_f32 v[82:83], v[82:83], v[66:67], v[94:95] op_sel_hi:[1,0,1]
	v_pk_fma_f32 v[84:85], v[84:85], v[66:67], v[96:97] op_sel_hi:[1,0,1]
	s_waitcnt lgkmcnt(0)
	v_mul_f32_e32 v94, v93, v83
	v_mul_f32_e32 v69, v91, v85
	v_fmac_f32_e32 v69, v90, v84
	v_fmac_f32_e32 v94, v92, v82
	v_add_f32_e32 v69, v69, v94
	v_pk_mul_f32 v[94:95], v[136:137], v[88:89] op_sel_hi:[0,1]
	v_pk_mul_f32 v[96:97], v[136:137], v[86:87] op_sel_hi:[0,1]
	v_pk_fma_f32 v[78:79], v[78:79], v[66:67], v[94:95] op_sel:[0,1,0]
	v_pk_fma_f32 v[80:81], v[80:81], v[66:67], v[96:97] op_sel:[0,1,0]
	v_mul_f32_e32 v67, v93, v79
	v_mul_f32_e32 v66, v91, v81
	v_fmac_f32_e32 v66, v90, v80
	v_fmac_f32_e32 v67, v92, v78
	v_add_f32_e32 v66, v66, v67
	v_add_f32_e32 v96, v172, v66
	v_pk_mul_f32 v[66:67], v[138:139], v[88:89] op_sel_hi:[0,1]
	v_pk_mul_f32 v[94:95], v[138:139], v[86:87] op_sel_hi:[0,1]
	v_pk_fma_f32 v[164:165], v[74:75], v[68:69], v[66:67] op_sel_hi:[1,0,1]
	v_pk_fma_f32 v[166:167], v[76:77], v[68:69], v[94:95] op_sel_hi:[1,0,1]
	v_mul_f32_e32 v67, v93, v165
	v_mul_f32_e32 v66, v91, v167
	v_fmac_f32_e32 v66, v90, v166
	v_fmac_f32_e32 v67, v92, v164
	v_add_f32_e32 v66, v66, v67
	v_add_f32_e32 v140, v151, v69
	v_add_f32_e32 v74, v173, v66
	v_pk_mul_f32 v[66:67], v[134:135], v[88:89] op_sel_hi:[0,1]
	v_pk_mul_f32 v[68:69], v[134:135], v[86:87] op_sel_hi:[0,1]
	v_pk_fma_f32 v[168:169], v[70:71], v[150:151], v[66:67] op_sel_hi:[1,0,1]
	v_pk_fma_f32 v[170:171], v[72:73], v[150:151], v[68:69] op_sel_hi:[1,0,1]
	v_mul_f32_e32 v67, v93, v169
	v_mul_f32_e32 v66, v91, v171
	v_fmac_f32_e32 v66, v90, v170
	v_fmac_f32_e32 v67, v92, v168
	v_add_f32_e32 v66, v66, v67
	s_nop 1
	v_add_f32_e32 v66, v174, v66
	s_waitcnt lgkmcnt(0)
	v_add_f32_dpp v67, v140, v140 quad_perm:[1,0,3,2] row_mask:0xf bank_mask:0xf
	s_nop 1
	s_waitcnt lgkmcnt(0)
	v_add_f32_dpp v67, v67, v67 quad_perm:[2,3,0,1] row_mask:0xf bank_mask:0xf
	s_nop 1
	s_waitcnt lgkmcnt(0)
	v_add_f32_dpp v67, v67, v67 row_half_mirror row_mask:0xf bank_mask:0xf
	v_cndmask_b32_e64 v177, v141, v67, s[56:57]
	s_nop 1
	s_waitcnt lgkmcnt(0)
	v_add_f32_dpp v67, v96, v96 quad_perm:[1,0,3,2] row_mask:0xf bank_mask:0xf
	s_nop 1
	s_waitcnt lgkmcnt(0)
	v_add_f32_dpp v67, v67, v67 quad_perm:[2,3,0,1] row_mask:0xf bank_mask:0xf
	s_nop 1
	s_waitcnt lgkmcnt(0)
	v_add_f32_dpp v67, v67, v67 row_half_mirror row_mask:0xf bank_mask:0xf
	v_cndmask_b32_e64 v179, v139, v67, s[56:57]
	s_nop 1
	s_waitcnt lgkmcnt(0)
	v_add_f32_dpp v67, v74, v74 quad_perm:[1,0,3,2] row_mask:0xf bank_mask:0xf
	s_nop 1
	s_waitcnt lgkmcnt(0)
	v_add_f32_dpp v67, v67, v67 quad_perm:[2,3,0,1] row_mask:0xf bank_mask:0xf
	s_nop 1
	s_waitcnt lgkmcnt(0)
	v_add_f32_dpp v67, v67, v67 row_half_mirror row_mask:0xf bank_mask:0xf
	v_cndmask_b32_e64 v181, v137, v67, s[56:57]
	s_nop 1
	s_waitcnt lgkmcnt(0)
	v_add_f32_dpp v66, v66, v66 quad_perm:[1,0,3,2] row_mask:0xf bank_mask:0xf
	s_nop 1
	s_waitcnt lgkmcnt(0)
	v_add_f32_dpp v66, v66, v66 quad_perm:[2,3,0,1] row_mask:0xf bank_mask:0xf
	s_nop 1
	s_waitcnt lgkmcnt(0)
	v_add_f32_dpp v66, v66, v66 row_half_mirror row_mask:0xf bank_mask:0xf
	v_cndmask_b32_e64 v182, v135, v66, s[56:57]
	ds_read_b128 v[66:69], v49 offset:16480
	ds_read_b128 v[172:175], v49 offset:16608
	ds_read2st64_b32 v[70:71], v201 offset0:24 offset1:25
	s_waitcnt lgkmcnt(1)
	v_mov_b32_e32 v180, v175
	s_waitcnt lgkmcnt(0)
	v_mul_f32_e32 v138, v66, v70
	v_mul_f32_e32 v150, v67, v71
	ds_read2st64_b32 v[66:67], v201 offset0:26 offset1:27
	ds_read_b128 v[86:89], v215 offset:11264
	ds_read_b128 v[90:93], v215 offset:15360
	s_waitcnt lgkmcnt(2)
	v_mul_f32_e32 v176, v68, v66
	v_mul_f32_e32 v178, v69, v67
	s_waitcnt lgkmcnt(1)
	v_pk_mul_f32 v[66:67], v[138:139], v[88:89] op_sel_hi:[0,1]
	v_pk_mul_f32 v[68:69], v[138:139], v[86:87] op_sel_hi:[0,1]
	v_pk_fma_f32 v[66:67], v[118:119], v[172:173], v[66:67] op_sel_hi:[1,0,1]
	v_pk_fma_f32 v[68:69], v[120:121], v[172:173], v[68:69] op_sel_hi:[1,0,1]
	s_waitcnt lgkmcnt(0)
	v_mul_f32_e32 v71, v93, v67
	v_mul_f32_e32 v70, v91, v69
	v_fmac_f32_e32 v70, v90, v68
	v_fmac_f32_e32 v71, v92, v66
	v_add_f32_e32 v70, v70, v71
	v_add_f32_e32 v96, 0, v70
	v_pk_mul_f32 v[70:71], v[88:89], v[150:151] op_sel_hi:[1,0]
	v_pk_mul_f32 v[72:73], v[86:87], v[150:151] op_sel_hi:[1,0]
	v_pk_fma_f32 v[70:71], v[122:123], v[172:173], v[70:71] op_sel:[0,1,0]
	v_pk_fma_f32 v[72:73], v[124:125], v[172:173], v[72:73] op_sel:[0,1,0]
	v_mul_f32_e32 v75, v93, v71
	v_mul_f32_e32 v74, v91, v73
	v_fmac_f32_e32 v74, v90, v72
	v_fmac_f32_e32 v75, v92, v70
	v_add_f32_e32 v74, v74, v75
	v_add_f32_e32 v134, 0, v74
	v_pk_mul_f32 v[74:75], v[88:89], v[176:177] op_sel_hi:[1,0]
	v_pk_mul_f32 v[76:77], v[86:87], v[176:177] op_sel_hi:[1,0]
	v_pk_fma_f32 v[74:75], v[126:127], v[174:175], v[74:75] op_sel_hi:[1,0,1]
	v_pk_fma_f32 v[76:77], v[128:129], v[174:175], v[76:77] op_sel_hi:[1,0,1]
	v_mul_f32_e32 v95, v93, v75
	v_mul_f32_e32 v94, v91, v77
	v_fmac_f32_e32 v94, v90, v76
	v_fmac_f32_e32 v95, v92, v74
	v_add_f32_e32 v94, v94, v95
	v_add_f32_e32 v126, 0, v94
	v_pk_mul_f32 v[88:89], v[88:89], v[178:179] op_sel_hi:[1,0]
	v_pk_mul_f32 v[94:95], v[86:87], v[178:179] op_sel_hi:[1,0]
	v_pk_fma_f32 v[86:87], v[130:131], v[180:181], v[88:89] op_sel_hi:[1,0,1]
	v_pk_fma_f32 v[88:89], v[132:133], v[180:181], v[94:95] op_sel_hi:[1,0,1]
	ds_read_b128 v[118:121], v215 offset:11392
	ds_read_b128 v[122:125], v215 offset:15488
	v_mul_f32_e32 v91, v91, v89
	v_fmac_f32_e32 v91, v90, v88
	v_mul_f32_e32 v90, v93, v87
	v_fmac_f32_e32 v90, v92, v86
	v_add_f32_e32 v90, v91, v90
	v_add_f32_e32 v127, 0, v90
	s_waitcnt lgkmcnt(1)
	v_pk_mul_f32 v[90:91], v[138:139], v[120:121] op_sel_hi:[0,1]
	v_pk_mul_f32 v[92:93], v[138:139], v[118:119] op_sel_hi:[0,1]
	v_pk_fma_f32 v[90:91], v[114:115], v[172:173], v[90:91] op_sel_hi:[1,0,1]
	v_pk_fma_f32 v[92:93], v[116:117], v[172:173], v[92:93] op_sel_hi:[1,0,1]
	s_waitcnt lgkmcnt(0)
	v_mul_f32_e32 v95, v125, v91
	v_mul_f32_e32 v94, v123, v93
	v_fmac_f32_e32 v94, v122, v92
	v_fmac_f32_e32 v95, v124, v90
	v_add_f32_e32 v94, v94, v95
	v_add_f32_e32 v128, v96, v94
	v_pk_mul_f32 v[94:95], v[150:151], v[120:121] op_sel_hi:[0,1]
	v_pk_mul_f32 v[96:97], v[150:151], v[118:119] op_sel_hi:[0,1]
	v_pk_fma_f32 v[94:95], v[110:111], v[172:173], v[94:95] op_sel:[0,1,0]
	v_pk_fma_f32 v[96:97], v[112:113], v[172:173], v[96:97] op_sel:[0,1,0]
	v_mul_f32_e32 v111, v125, v95
	v_mul_f32_e32 v110, v123, v97
	v_fmac_f32_e32 v110, v122, v96
	v_fmac_f32_e32 v111, v124, v94
	v_add_f32_e32 v110, v110, v111
	v_add_f32_e32 v130, v134, v110
	v_pk_mul_f32 v[110:111], v[176:177], v[120:121] op_sel_hi:[0,1]
	v_pk_mul_f32 v[112:113], v[176:177], v[118:119] op_sel_hi:[0,1]
	v_pk_fma_f32 v[114:115], v[106:107], v[174:175], v[110:111] op_sel_hi:[1,0,1]
	v_pk_fma_f32 v[116:117], v[108:109], v[174:175], v[112:113] op_sel_hi:[1,0,1]
	v_mul_f32_e32 v107, v125, v115
	v_mul_f32_e32 v106, v123, v117
	v_fmac_f32_e32 v106, v122, v116
	v_fmac_f32_e32 v107, v124, v114
	v_add_f32_e32 v106, v106, v107
	v_add_f32_e32 v134, v126, v106
	v_pk_mul_f32 v[106:107], v[120:121], v[178:179] op_sel_hi:[1,0]
	v_pk_mul_f32 v[108:109], v[118:119], v[178:179] op_sel_hi:[1,0]
	v_pk_fma_f32 v[118:119], v[102:103], v[180:181], v[106:107] op_sel_hi:[1,0,1]
	v_pk_fma_f32 v[120:121], v[104:105], v[180:181], v[108:109] op_sel_hi:[1,0,1]
	v_mul_f32_e32 v103, v125, v119
	v_mul_f32_e32 v102, v123, v121
	v_fmac_f32_e32 v102, v122, v120
	v_fmac_f32_e32 v103, v124, v118
	v_add_f32_e32 v102, v102, v103
	v_add_f32_e32 v139, v102, v127
	ds_read_b128 v[102:105], v215 offset:11520
	ds_read_b128 v[106:109], v215 offset:15616
	s_waitcnt lgkmcnt(1)
	v_pk_mul_f32 v[110:111], v[138:139], v[104:105] op_sel_hi:[0,1]
	v_pk_mul_f32 v[112:113], v[138:139], v[102:103] op_sel_hi:[0,1]
	v_pk_fma_f32 v[122:123], v[152:153], v[172:173], v[110:111] op_sel_hi:[1,0,1]
	v_pk_fma_f32 v[124:125], v[154:155], v[172:173], v[112:113] op_sel_hi:[1,0,1]
	s_waitcnt lgkmcnt(0)
	v_mul_f32_e32 v111, v109, v123
	v_mul_f32_e32 v110, v107, v125
	v_fmac_f32_e32 v110, v106, v124
	v_fmac_f32_e32 v111, v108, v122
	v_add_f32_e32 v110, v110, v111
	v_add_f32_e32 v151, v128, v110
	v_pk_mul_f32 v[110:111], v[150:151], v[104:105] op_sel_hi:[0,1]
	v_pk_mul_f32 v[112:113], v[150:151], v[102:103] op_sel_hi:[0,1]
	v_pk_fma_f32 v[126:127], v[156:157], v[172:173], v[110:111] op_sel:[0,1,0]
	v_pk_fma_f32 v[128:129], v[158:159], v[172:173], v[112:113] op_sel:[0,1,0]
	v_mul_f32_e32 v111, v109, v127
	v_mul_f32_e32 v110, v107, v129
	v_fmac_f32_e32 v110, v106, v128
	v_fmac_f32_e32 v111, v108, v126
	v_add_f32_e32 v110, v110, v111
	v_add_f32_e32 v154, v130, v110
	v_pk_mul_f32 v[110:111], v[176:177], v[104:105] op_sel_hi:[0,1]
	v_pk_mul_f32 v[112:113], v[176:177], v[102:103] op_sel_hi:[0,1]
	v_pk_fma_f32 v[130:131], v[160:161], v[174:175], v[110:111] op_sel_hi:[1,0,1]
	v_pk_fma_f32 v[132:133], v[162:163], v[174:175], v[112:113] op_sel_hi:[1,0,1]
	v_mul_f32_e32 v111, v109, v131
	v_mul_f32_e32 v110, v107, v133
	v_fmac_f32_e32 v110, v106, v132
	v_fmac_f32_e32 v111, v108, v130
	v_add_f32_e32 v110, v110, v111
	v_pk_mul_f32 v[104:105], v[178:179], v[104:105] op_sel_hi:[0,1]
	v_pk_mul_f32 v[102:103], v[178:179], v[102:103] op_sel_hi:[0,1]
	v_add_f32_e32 v110, v134, v110
	v_pk_fma_f32 v[134:135], v[98:99], v[180:181], v[104:105] op_sel_hi:[1,0,1]
	v_pk_fma_f32 v[136:137], v[100:101], v[180:181], v[102:103] op_sel_hi:[1,0,1]
	v_mul_f32_e32 v99, v109, v135
	v_mul_f32_e32 v98, v107, v137
	v_fmac_f32_e32 v98, v106, v136
	v_fmac_f32_e32 v99, v108, v134
	v_add_f32_e32 v98, v98, v99
	v_add_f32_e32 v111, v139, v98
	ds_read_b128 v[98:101], v215 offset:11648
	ds_read_b128 v[102:105], v215 offset:15744
	s_waitcnt lgkmcnt(1)
	v_pk_mul_f32 v[106:107], v[138:139], v[100:101] op_sel_hi:[0,1]
	v_pk_mul_f32 v[108:109], v[138:139], v[98:99] op_sel_hi:[0,1]
	v_pk_fma_f32 v[138:139], v[82:83], v[172:173], v[106:107] op_sel_hi:[1,0,1]
	v_pk_fma_f32 v[140:141], v[84:85], v[172:173], v[108:109] op_sel_hi:[1,0,1]
	s_waitcnt lgkmcnt(0)
	v_mul_f32_e32 v83, v105, v139
	v_mul_f32_e32 v82, v103, v141
	v_fmac_f32_e32 v82, v102, v140
	v_fmac_f32_e32 v83, v104, v138
	v_add_f32_e32 v82, v82, v83
	v_add_f32_e32 v106, v151, v82
	v_pk_mul_f32 v[82:83], v[150:151], v[100:101] op_sel_hi:[0,1]
	v_pk_mul_f32 v[84:85], v[150:151], v[98:99] op_sel_hi:[0,1]
	v_pk_fma_f32 v[150:151], v[78:79], v[172:173], v[82:83] op_sel:[0,1,0]
	v_pk_fma_f32 v[152:153], v[80:81], v[172:173], v[84:85] op_sel:[0,1,0]
	v_mul_f32_e32 v79, v105, v151
	v_mul_f32_e32 v78, v103, v153
	v_fmac_f32_e32 v78, v102, v152
	v_fmac_f32_e32 v79, v104, v150
	v_add_f32_e32 v78, v78, v79
	v_add_f32_e32 v82, v154, v78
	v_pk_mul_f32 v[78:79], v[176:177], v[100:101] op_sel_hi:[0,1]
	v_pk_mul_f32 v[80:81], v[176:177], v[98:99] op_sel_hi:[0,1]
	v_pk_fma_f32 v[154:155], v[164:165], v[174:175], v[78:79] op_sel_hi:[1,0,1]
	v_pk_fma_f32 v[156:157], v[166:167], v[174:175], v[80:81] op_sel_hi:[1,0,1]
	v_mul_f32_e32 v79, v105, v155
	v_mul_f32_e32 v78, v103, v157
	v_fmac_f32_e32 v78, v102, v156
	v_fmac_f32_e32 v79, v104, v154
	v_add_f32_e32 v78, v78, v79
	v_add_f32_e32 v83, v110, v78
	v_pk_mul_f32 v[78:79], v[178:179], v[100:101] op_sel_hi:[0,1]
	v_pk_mul_f32 v[80:81], v[178:179], v[98:99] op_sel_hi:[0,1]
	v_pk_fma_f32 v[158:159], v[168:169], v[180:181], v[78:79] op_sel_hi:[1,0,1]
	v_pk_fma_f32 v[160:161], v[170:171], v[180:181], v[80:81] op_sel_hi:[1,0,1]
	v_mul_f32_e32 v79, v105, v159
	v_mul_f32_e32 v78, v103, v161
	v_fmac_f32_e32 v78, v102, v160
	v_fmac_f32_e32 v79, v104, v158
	v_add_f32_e32 v78, v78, v79
	s_nop 1
	v_add_f32_e32 v78, v111, v78
	s_waitcnt lgkmcnt(0)
	v_add_f32_dpp v79, v106, v106 quad_perm:[1,0,3,2] row_mask:0xf bank_mask:0xf
	s_nop 1
	s_waitcnt lgkmcnt(0)
	v_add_f32_dpp v79, v79, v79 quad_perm:[2,3,0,1] row_mask:0xf bank_mask:0xf
	s_nop 1
	s_waitcnt lgkmcnt(0)
	v_add_f32_dpp v79, v79, v79 row_half_mirror row_mask:0xf bank_mask:0xf
	v_cndmask_b32_e64 v163, v177, v79, s[58:59]
	s_nop 1
	s_waitcnt lgkmcnt(0)
	v_add_f32_dpp v79, v82, v82 quad_perm:[1,0,3,2] row_mask:0xf bank_mask:0xf
	s_nop 1
	s_waitcnt lgkmcnt(0)
	v_add_f32_dpp v79, v79, v79 quad_perm:[2,3,0,1] row_mask:0xf bank_mask:0xf
	s_nop 1
	s_waitcnt lgkmcnt(0)
	v_add_f32_dpp v79, v79, v79 row_half_mirror row_mask:0xf bank_mask:0xf
	v_cndmask_b32_e64 v165, v179, v79, s[58:59]
	s_nop 1
	s_waitcnt lgkmcnt(0)
	v_add_f32_dpp v79, v83, v83 quad_perm:[1,0,3,2] row_mask:0xf bank_mask:0xf
	s_nop 1
	s_waitcnt lgkmcnt(0)
	v_add_f32_dpp v79, v79, v79 quad_perm:[2,3,0,1] row_mask:0xf bank_mask:0xf
	s_nop 1
	s_waitcnt lgkmcnt(0)
	v_add_f32_dpp v79, v79, v79 row_half_mirror row_mask:0xf bank_mask:0xf
	v_cndmask_b32_e64 v167, v181, v79, s[58:59]
	s_nop 1
	s_waitcnt lgkmcnt(0)
	v_add_f32_dpp v78, v78, v78 quad_perm:[1,0,3,2] row_mask:0xf bank_mask:0xf
	s_nop 1
	s_waitcnt lgkmcnt(0)
	v_add_f32_dpp v78, v78, v78 quad_perm:[2,3,0,1] row_mask:0xf bank_mask:0xf
	s_nop 1
	s_waitcnt lgkmcnt(0)
	v_add_f32_dpp v78, v78, v78 row_half_mirror row_mask:0xf bank_mask:0xf
	v_cndmask_b32_e64 v169, v182, v78, s[58:59]
	ds_read_b128 v[82:85], v49 offset:16496
	ds_read_b128 v[78:81], v49 offset:16624
	ds_read2st64_b32 v[98:99], v201 offset0:28 offset1:29
	s_waitcnt lgkmcnt(1)
	v_mov_b32_e32 v170, v81
	s_waitcnt lgkmcnt(0)
	v_mul_f32_e32 v168, v82, v98
	v_mul_f32_e32 v166, v83, v99
	ds_read2st64_b32 v[82:83], v201 offset0:30 offset1:31
	ds_read_b128 v[106:109], v215 offset:11776
	ds_read_b128 v[110:113], v215 offset:15872
	s_waitcnt lgkmcnt(2)
	v_mul_f32_e32 v164, v84, v82
	v_mul_f32_e32 v162, v85, v83
	s_waitcnt lgkmcnt(1)
	v_pk_mul_f32 v[82:83], v[168:169], v[108:109] op_sel_hi:[0,1]
	v_pk_mul_f32 v[84:85], v[168:169], v[106:107] op_sel_hi:[0,1]
	v_pk_fma_f32 v[104:105], v[66:67], v[78:79], v[82:83] op_sel_hi:[1,0,1]
	v_pk_fma_f32 v[102:103], v[68:69], v[78:79], v[84:85] op_sel_hi:[1,0,1]
	s_waitcnt lgkmcnt(0)
	v_mul_f32_e32 v67, v113, v105
	v_mul_f32_e32 v66, v111, v103
	v_fmac_f32_e32 v66, v110, v102
	v_fmac_f32_e32 v67, v112, v104
	v_add_f32_e32 v66, v66, v67
	v_add_f32_e32 v171, 0, v66
	v_pk_mul_f32 v[66:67], v[108:109], v[166:167] op_sel_hi:[1,0]
	v_pk_mul_f32 v[68:69], v[106:107], v[166:167] op_sel_hi:[1,0]
	v_pk_fma_f32 v[100:101], v[70:71], v[78:79], v[66:67] op_sel:[0,1,0]
	v_pk_fma_f32 v[98:99], v[72:73], v[78:79], v[68:69] op_sel:[0,1,0]
	v_mul_f32_e32 v67, v113, v101
	v_mul_f32_e32 v66, v111, v99
	v_fmac_f32_e32 v66, v110, v98
	v_fmac_f32_e32 v67, v112, v100
	v_add_f32_e32 v66, v66, v67
	v_add_f32_e32 v172, 0, v66
	v_pk_mul_f32 v[66:67], v[108:109], v[164:165] op_sel_hi:[1,0]
	v_pk_mul_f32 v[68:69], v[106:107], v[164:165] op_sel_hi:[1,0]
	v_pk_fma_f32 v[84:85], v[74:75], v[80:81], v[66:67] op_sel_hi:[1,0,1]
	v_pk_fma_f32 v[82:83], v[76:77], v[80:81], v[68:69] op_sel_hi:[1,0,1]
	v_mul_f32_e32 v67, v113, v85
	v_mul_f32_e32 v66, v111, v83
	v_fmac_f32_e32 v66, v110, v82
	v_fmac_f32_e32 v67, v112, v84
	v_add_f32_e32 v66, v66, v67
	v_add_f32_e32 v173, 0, v66
	v_pk_mul_f32 v[66:67], v[108:109], v[162:163] op_sel_hi:[1,0]
	v_pk_mul_f32 v[70:71], v[106:107], v[162:163] op_sel_hi:[1,0]
	v_pk_fma_f32 v[68:69], v[86:87], v[170:171], v[66:67] op_sel_hi:[1,0,1]
	v_pk_fma_f32 v[66:67], v[88:89], v[170:171], v[70:71] op_sel_hi:[1,0,1]
	v_mul_f32_e32 v71, v113, v69
	v_mul_f32_e32 v70, v111, v67
	v_fmac_f32_e32 v70, v110, v66
	v_fmac_f32_e32 v71, v112, v68
	v_add_f32_e32 v70, v70, v71
	v_add_f32_e32 v174, 0, v70
	ds_read_b128 v[70:73], v215 offset:11904
	ds_read_b128 v[74:77], v215 offset:16000
	s_waitcnt lgkmcnt(1)
	v_pk_mul_f32 v[86:87], v[168:169], v[72:73] op_sel_hi:[0,1]
	v_pk_mul_f32 v[88:89], v[168:169], v[70:71] op_sel_hi:[0,1]
	v_pk_fma_f32 v[112:113], v[90:91], v[78:79], v[86:87] op_sel_hi:[1,0,1]
	v_pk_fma_f32 v[110:111], v[92:93], v[78:79], v[88:89] op_sel_hi:[1,0,1]
	s_waitcnt lgkmcnt(0)
	v_mul_f32_e32 v87, v77, v113
	v_mul_f32_e32 v86, v75, v111
	v_fmac_f32_e32 v86, v74, v110
	v_fmac_f32_e32 v87, v76, v112
	v_add_f32_e32 v86, v86, v87
	v_add_f32_e32 v171, v171, v86
	v_pk_mul_f32 v[86:87], v[166:167], v[72:73] op_sel_hi:[0,1]
	v_pk_mul_f32 v[88:89], v[166:167], v[70:71] op_sel_hi:[0,1]
	v_pk_fma_f32 v[108:109], v[94:95], v[78:79], v[86:87] op_sel:[0,1,0]
	v_pk_fma_f32 v[106:107], v[96:97], v[78:79], v[88:89] op_sel:[0,1,0]
	v_mul_f32_e32 v87, v77, v109
	v_mul_f32_e32 v86, v75, v107
	v_fmac_f32_e32 v86, v74, v106
	v_fmac_f32_e32 v87, v76, v108
	v_add_f32_e32 v86, v86, v87
	v_add_f32_e32 v172, v172, v86
	v_pk_mul_f32 v[86:87], v[164:165], v[72:73] op_sel_hi:[0,1]
	v_pk_mul_f32 v[90:91], v[164:165], v[70:71] op_sel_hi:[0,1]
	v_pk_mul_f32 v[70:71], v[70:71], v[162:163] op_sel_hi:[1,0]
	v_pk_fma_f32 v[88:89], v[114:115], v[80:81], v[86:87] op_sel_hi:[1,0,1]
	v_pk_fma_f32 v[86:87], v[116:117], v[80:81], v[90:91] op_sel_hi:[1,0,1]
	v_pk_mul_f32 v[72:73], v[72:73], v[162:163] op_sel_hi:[1,0]
	v_pk_fma_f32 v[70:71], v[120:121], v[170:171], v[70:71] op_sel_hi:[1,0,1]
	v_mul_f32_e32 v90, v75, v87
	v_pk_fma_f32 v[72:73], v[118:119], v[170:171], v[72:73] op_sel_hi:[1,0,1]
	v_mul_f32_e32 v75, v75, v71
	v_fmac_f32_e32 v90, v74, v86
	v_fmac_f32_e32 v75, v74, v70
	v_mul_f32_e32 v74, v77, v73
	v_fmac_f32_e32 v74, v76, v72
	v_mul_f32_e32 v91, v77, v89
	v_add_f32_e32 v74, v75, v74
	v_fmac_f32_e32 v91, v76, v88
	v_add_f32_e32 v174, v74, v174
	ds_read_b128 v[74:77], v215 offset:12032
	ds_read_b128 v[94:97], v215 offset:16128
	v_add_f32_e32 v90, v90, v91
	v_add_f32_e32 v173, v173, v90
	s_waitcnt lgkmcnt(1)
	v_pk_mul_f32 v[90:91], v[168:169], v[76:77] op_sel_hi:[0,1]
	v_pk_mul_f32 v[92:93], v[168:169], v[74:75] op_sel_hi:[0,1]
	v_pk_fma_f32 v[120:121], v[122:123], v[78:79], v[90:91] op_sel_hi:[1,0,1]
	v_pk_fma_f32 v[118:119], v[124:125], v[78:79], v[92:93] op_sel_hi:[1,0,1]
	s_waitcnt lgkmcnt(0)
	v_mul_f32_e32 v91, v97, v121
	v_mul_f32_e32 v90, v95, v119
	v_fmac_f32_e32 v90, v94, v118
	v_fmac_f32_e32 v91, v96, v120
	v_add_f32_e32 v90, v90, v91
	v_add_f32_e32 v124, v171, v90
	v_pk_mul_f32 v[90:91], v[166:167], v[76:77] op_sel_hi:[0,1]
	v_pk_mul_f32 v[92:93], v[166:167], v[74:75] op_sel_hi:[0,1]
	v_pk_fma_f32 v[116:117], v[126:127], v[78:79], v[90:91] op_sel:[0,1,0]
	v_pk_fma_f32 v[114:115], v[128:129], v[78:79], v[92:93] op_sel:[0,1,0]
	v_mul_f32_e32 v91, v97, v117
	v_mul_f32_e32 v90, v95, v115
	v_fmac_f32_e32 v90, v94, v114
	v_fmac_f32_e32 v91, v96, v116
	v_add_f32_e32 v90, v90, v91
	v_add_f32_e32 v171, v172, v90
	v_pk_mul_f32 v[90:91], v[164:165], v[76:77] op_sel_hi:[0,1]
	v_pk_mul_f32 v[122:123], v[164:165], v[74:75] op_sel_hi:[0,1]
	v_pk_mul_f32 v[74:75], v[162:163], v[74:75] op_sel_hi:[0,1]
	v_pk_fma_f32 v[92:93], v[130:131], v[80:81], v[90:91] op_sel_hi:[1,0,1]
	v_pk_fma_f32 v[90:91], v[132:133], v[80:81], v[122:123] op_sel_hi:[1,0,1]
	v_pk_mul_f32 v[76:77], v[162:163], v[76:77] op_sel_hi:[0,1]
	v_pk_fma_f32 v[74:75], v[136:137], v[170:171], v[74:75] op_sel_hi:[1,0,1]
	v_mul_f32_e32 v122, v95, v91
	v_pk_fma_f32 v[76:77], v[134:135], v[170:171], v[76:77] op_sel_hi:[1,0,1]
	v_mul_f32_e32 v95, v95, v75
	ds_read_b128 v[130:133], v215 offset:12160
	ds_read_b128 v[134:137], v215 offset:16256
	v_fmac_f32_e32 v122, v94, v90
	v_mul_f32_e32 v123, v97, v93
	v_fmac_f32_e32 v95, v94, v74
	v_mul_f32_e32 v94, v97, v77
	v_fmac_f32_e32 v123, v96, v92
	v_fmac_f32_e32 v94, v96, v76
	v_add_f32_e32 v122, v122, v123
	v_add_f32_e32 v94, v95, v94
	v_add_f32_e32 v172, v173, v122
	v_add_f32_e32 v173, v174, v94
	s_waitcnt lgkmcnt(1)
	v_pk_mul_f32 v[94:95], v[168:169], v[132:133] op_sel_hi:[0,1]
	v_pk_mul_f32 v[96:97], v[168:169], v[130:131] op_sel_hi:[0,1]
	v_pk_fma_f32 v[128:129], v[138:139], v[78:79], v[94:95] op_sel_hi:[1,0,1]
	v_pk_fma_f32 v[126:127], v[140:141], v[78:79], v[96:97] op_sel_hi:[1,0,1]
	s_waitcnt lgkmcnt(0)
	v_mul_f32_e32 v95, v137, v129
	v_mul_f32_e32 v94, v135, v127
	v_fmac_f32_e32 v94, v134, v126
	v_fmac_f32_e32 v95, v136, v128
	v_add_f32_e32 v94, v94, v95
	v_add_f32_e32 v138, v124, v94
	v_pk_mul_f32 v[94:95], v[166:167], v[132:133] op_sel_hi:[0,1]
	v_pk_mul_f32 v[96:97], v[166:167], v[130:131] op_sel_hi:[0,1]
	v_pk_fma_f32 v[124:125], v[150:151], v[78:79], v[94:95] op_sel:[0,1,0]
	v_pk_fma_f32 v[122:123], v[152:153], v[78:79], v[96:97] op_sel:[0,1,0]
	v_mul_f32_e32 v79, v137, v125
	v_mul_f32_e32 v78, v135, v123
	v_fmac_f32_e32 v78, v134, v122
	v_fmac_f32_e32 v79, v136, v124
	v_add_f32_e32 v78, v78, v79
	v_add_f32_e32 v139, v171, v78
	v_pk_mul_f32 v[78:79], v[164:165], v[132:133] op_sel_hi:[0,1]
	v_pk_mul_f32 v[94:95], v[164:165], v[130:131] op_sel_hi:[0,1]
	v_pk_fma_f32 v[96:97], v[154:155], v[80:81], v[78:79] op_sel_hi:[1,0,1]
	v_pk_fma_f32 v[94:95], v[156:157], v[80:81], v[94:95] op_sel_hi:[1,0,1]
	v_mul_f32_e32 v79, v137, v97
	v_mul_f32_e32 v78, v135, v95
	v_fmac_f32_e32 v78, v134, v94
	v_fmac_f32_e32 v79, v136, v96
	v_add_f32_e32 v78, v78, v79
	v_add_f32_e32 v141, v172, v78
	v_pk_mul_f32 v[78:79], v[162:163], v[132:133] op_sel_hi:[0,1]
	v_pk_mul_f32 v[130:131], v[162:163], v[130:131] op_sel_hi:[0,1]
	v_pk_fma_f32 v[80:81], v[158:159], v[170:171], v[78:79] op_sel_hi:[1,0,1]
	v_pk_fma_f32 v[78:79], v[160:161], v[170:171], v[130:131] op_sel_hi:[1,0,1]
	v_mul_f32_e32 v131, v137, v81
	v_mul_f32_e32 v130, v135, v79
	v_fmac_f32_e32 v130, v134, v78
	v_fmac_f32_e32 v131, v136, v80
	v_add_f32_e32 v130, v130, v131
	s_nop 1
	v_add_f32_e32 v130, v173, v130
	ds_read2st64_b32 v[136:137], v220 offset1:1
	s_waitcnt lgkmcnt(1)
	v_add_f32_dpp v131, v138, v138 quad_perm:[1,0,3,2] row_mask:0xf bank_mask:0xf
	s_nop 1
	s_waitcnt lgkmcnt(0)
	v_add_f32_dpp v131, v131, v131 quad_perm:[2,3,0,1] row_mask:0xf bank_mask:0xf
	s_nop 1
	s_waitcnt lgkmcnt(0)
	v_add_f32_dpp v131, v131, v131 row_half_mirror row_mask:0xf bank_mask:0xf
	v_cndmask_b32_e64 v133, v163, v131, s[60:61]
	s_nop 1
	s_waitcnt lgkmcnt(0)
	v_add_f32_dpp v131, v139, v139 quad_perm:[1,0,3,2] row_mask:0xf bank_mask:0xf
	s_nop 1
	s_waitcnt lgkmcnt(0)
	v_add_f32_dpp v131, v131, v131 quad_perm:[2,3,0,1] row_mask:0xf bank_mask:0xf
	s_nop 1
	s_waitcnt lgkmcnt(0)
	v_add_f32_dpp v131, v131, v131 row_half_mirror row_mask:0xf bank_mask:0xf
	v_cndmask_b32_e64 v140, v165, v131, s[60:61]
	s_nop 1
	s_waitcnt lgkmcnt(0)
	v_add_f32_dpp v131, v141, v141 quad_perm:[1,0,3,2] row_mask:0xf bank_mask:0xf
	s_nop 1
	s_waitcnt lgkmcnt(0)
	v_add_f32_dpp v131, v131, v131 quad_perm:[2,3,0,1] row_mask:0xf bank_mask:0xf
	s_nop 1
	s_waitcnt lgkmcnt(0)
	v_add_f32_dpp v131, v131, v131 row_half_mirror row_mask:0xf bank_mask:0xf
	v_cndmask_b32_e64 v139, v167, v131, s[60:61]
	s_nop 1
	v_add_u32_e32 v132, s6, v142
	s_waitcnt lgkmcnt(0)
	v_add_f32_dpp v130, v130, v130 quad_perm:[1,0,3,2] row_mask:0xf bank_mask:0xf
	s_nop 1
	s_waitcnt lgkmcnt(0)
	v_add_f32_dpp v130, v130, v130 quad_perm:[2,3,0,1] row_mask:0xf bank_mask:0xf
	s_nop 1
	s_waitcnt lgkmcnt(0)
	v_add_f32_dpp v130, v130, v130 row_half_mirror row_mask:0xf bank_mask:0xf
	v_cndmask_b32_e64 v138, v169, v130, s[60:61]
	v_lshlrev_b64 v[130:131], 12, v[148:149]
	v_lshl_add_u64 v[134:135], s[70:71], 0, v[130:131]
	v_lshl_add_u64 v[130:131], v[144:145], 2, s[0:1]
	s_lshl_b64 s[0:1], s[64:65], 2
	s_add_u32 s0, s24, s0
	s_addc_u32 s1, s25, s1
	v_lshl_add_u64 v[130:131], v[130:131], 0, v[48:49]
	s_load_dwordx2 s[98:99], s[0:1], 0x0
	s_load_dwordx2 s[100:101], s[0:1], 0x8
	ds_read2st64_b32 v[246:247], v220 offset0:2 offset1:3
	s_add_i32 s9, s9, s36
	s_mov_b32 s64, 0x3f2aaaab
	s_waitcnt vmcnt(0) lgkmcnt(0)
	v_fmac_f32_e32 v133, s98, v136
	v_fmac_f32_e32 v140, s99, v137
	v_fmac_f32_e32 v139, s100, v246
	v_fmac_f32_e32 v138, s101, v247
	v_lshlrev_b32_e32 v223, 16, v223
	v_lshlrev_b32_e32 v222, 16, v222
	v_lshlrev_b32_e32 v221, 16, v221
	v_lshlrev_b32_e32 v207, 16, v207
	v_mul_f32_e32 v136, 0xbfb8aa3b, v223
	v_mul_f32_e32 v137, 0xbfb8aa3b, v222
	v_mul_f32_e32 v246, 0xbfb8aa3b, v221
	v_mul_f32_e32 v247, 0xbfb8aa3b, v207
	v_exp_f32_e32 v136, v136
	v_exp_f32_e32 v137, v137
	v_exp_f32_e32 v246, v246
	v_exp_f32_e32 v247, v247
	v_add_f32_e32 v136, 1.0, v136
	v_add_f32_e32 v137, 1.0, v137
	v_add_f32_e32 v246, 1.0, v246
	v_add_f32_e32 v247, 1.0, v247
	v_rcp_f32_e32 v136, v136
	v_rcp_f32_e32 v137, v137
	v_rcp_f32_e32 v246, v246
	v_rcp_f32_e32 v247, v247
	v_mul_f32_e32 v223, v136, v223
	v_mul_f32_e32 v222, v137, v222
	v_mul_f32_e32 v221, v246, v221
	v_mul_f32_e32 v207, v247, v207
	v_mul_f32_e32 v133, v223, v133
	v_mul_f32_e32 v140, v222, v140
	v_mul_f32_e32 v139, v221, v139
	v_mul_f32_e32 v138, v207, v138
	v_cvt_pk_bf16_f32 v48, v133, v49
	v_cvt_pk_bf16_f32 v140, v140, v49
	v_cvt_pk_bf16_f32 v139, v139, v49
	v_cvt_pk_bf16_f32 v138, v138, v49
	v_ashrrev_i32_e32 v133, 31, v132
	v_lshl_add_u64 v[132:133], v[132:133], 1, v[134:135]
	s_and_b64 vcc, exec, s[40:41]
	s_cbranch_vccnz .Lsm_nopf
	v_readlane_b32 s22, v252, 12
	v_readlane_b32 s23, v252, 13
	s_ashr_i32 s0, s62, 3
	s_add_i32 s0, s0, s8
	s_mul_i32 s0, s0, 0xc000
	s_add_u32 s6, s22, s0
	s_addc_u32 s7, s23, 0
	v_lshlrev_b32_e32 v244, 2, v245
	global_load_dword v246, v244, s[6:7]
	s_add_u32 s6, s6, 0x4000
	s_addc_u32 s7, s7, 0
	global_load_dword v247, v244, s[6:7]
	s_add_u32 s6, s6, 0x4000
	s_addc_u32 s7, s7, 0
	global_load_dword v248, v244, s[6:7]
	s_and_b32 s21, s62, -8
	s_mul_i32 s22, s21, 0x3000
	s_movk_i32 s23, 0x1000
	v_lshl_add_u32 v244, v245, 1, s23
	s_add_i32 s23, s22, 0xc000000
	s_add_u32 s6, s4, s23
	s_addc_u32 s7, s5, 0
	global_load_ushort v249, v244, s[6:7]
	s_add_i32 s23, s22, 0xc003000
	s_add_u32 s6, s4, s23
	s_addc_u32 s7, s5, 0
	global_load_ushort v250, v244, s[6:7]
	s_add_i32 s23, s22, 0xc006000
	s_add_u32 s6, s4, s23
	s_addc_u32 s7, s5, 0
	global_load_ushort v251, v244, s[6:7]
	s_add_i32 s23, s22, 0xc009000
	s_add_u32 s6, s4, s23
	s_addc_u32 s7, s5, 0
	global_load_ushort v241, v244, s[6:7]
	s_add_i32 s23, s22, 0xc00c000
	s_add_u32 s6, s4, s23
	s_addc_u32 s7, s5, 0
	global_load_ushort v216, v244, s[6:7]
	s_add_i32 s23, s22, 0xc00f000
	s_add_u32 s6, s4, s23
	s_addc_u32 s7, s5, 0
	global_load_ushort v217, v244, s[6:7]
	s_add_i32 s23, s22, 0xc012000
	s_add_u32 s6, s4, s23
	s_addc_u32 s7, s5, 0
	global_load_ushort v218, v244, s[6:7]
	s_add_i32 s23, s22, 0xc015000
	s_add_u32 s6, s4, s23
	s_addc_u32 s7, s5, 0
	global_load_ushort v242, v244, s[6:7]
	s_add_i32 s1, s21, 0x4000
	s_and_b32 s0, s62, 7
	v_add_u32_e32 v243, s1, v213
	v_lshlrev_b32_e32 v243, 7, v243
	v_lshl_or_b32 v244, s0, 2, v214
	v_lshl_add_u32 v243, v244, 2, v243
	v_readlane_b32 s6, v255, 8
	v_readlane_b32 s7, v255, 9
	s_nop 4
	global_load_dword v243, v243, s[6:7]
.Lsm_nopf:
	global_store_short v[132:133], v48, off
	global_store_dwordx4 v[130:131], v[102:105], off
	global_store_dwordx4 v[130:131], v[110:113], off offset:128
	global_store_dwordx4 v[130:131], v[118:121], off offset:256
	global_store_dwordx4 v[130:131], v[126:129], off offset:384
	s_nop 1
	v_mov_b64_e32 v[112:113], v[26:27]
	v_mov_b64_e32 v[128:129], v[30:31]
	v_mov_b64_e32 v[120:121], v[60:61]
	v_mov_b64_e32 v[126:127], v[28:29]
	v_mov_b64_e32 v[110:111], v[24:25]
	v_mov_b64_e32 v[118:119], v[58:59]
	v_mov_b64_e32 v[136:137], v[64:65]
	v_mov_b64_e32 v[134:135], v[62:63]
	v_add_co_u32_e32 v102, vcc, s17, v130
	s_nop 1
	v_addc_co_u32_e32 v103, vcc, 0, v131, vcc
	global_store_short v[132:133], v140, off offset:128
	global_store_dwordx4 v[102:103], v[98:101], off
	global_store_dwordx4 v[102:103], v[106:109], off offset:128
	global_store_dwordx4 v[102:103], v[114:117], off offset:256
	global_store_dwordx4 v[102:103], v[122:125], off offset:384
	s_nop 1
	v_add_co_u32_e32 v100, vcc, s13, v130
	s_nop 1
	v_addc_co_u32_e32 v101, vcc, 0, v131, vcc
	v_mov_b64_e32 v[124:125], v[14:15]
	v_mov_b64_e32 v[108:109], v[10:11]
	v_mov_b64_e32 v[116:117], v[42:43]
	v_mov_b64_e32 v[104:105], v[56:57]
	v_mov_b64_e32 v[122:123], v[12:13]
	v_mov_b64_e32 v[106:107], v[8:9]
	v_mov_b64_e32 v[114:115], v[40:41]
	v_mov_b64_e32 v[102:103], v[54:55]
	global_store_short v[132:133], v139, off offset:256
	global_store_dwordx4 v[100:101], v[82:85], off
	global_store_dwordx4 v[100:101], v[86:89], off offset:128
	global_store_dwordx4 v[100:101], v[90:93], off offset:256
	global_store_dwordx4 v[100:101], v[94:97], off offset:384
	s_nop 1
	v_mov_b64_e32 v[92:93], v[6:7]
	v_mov_b64_e32 v[96:97], v[22:23]
	v_mov_b64_e32 v[88:89], v[52:53]
	v_mov_b64_e32 v[90:91], v[4:5]
	v_mov_b64_e32 v[94:95], v[20:21]
	v_mov_b64_e32 v[86:87], v[50:51]
	v_mov_b64_e32 v[100:101], v[38:39]
	v_mov_b64_e32 v[98:99], v[36:37]
	v_add_co_u32_e32 v82, vcc, s37, v130
	s_nop 1
	v_addc_co_u32_e32 v83, vcc, 0, v131, vcc
	global_store_short v[132:133], v138, off offset:384
	global_store_dwordx4 v[82:83], v[66:69], off
	global_store_dwordx4 v[82:83], v[70:73], off offset:128
	global_store_dwordx4 v[82:83], v[74:77], off offset:256
	global_store_dwordx4 v[82:83], v[78:81], off offset:384
	s_nop 1
	v_mov_b64_e32 v[132:133], v[46:47]
	v_mov_b64_e32 v[76:77], v[2:3]
	v_mov_b64_e32 v[80:81], v[18:19]
	v_mov_b64_e32 v[84:85], v[34:35]
	s_andn2_b64 vcc, exec, s[40:41]
	v_mov_b64_e32 v[74:75], v[0:1]
	v_mov_b64_e32 v[78:79], v[16:17]
	v_mov_b64_e32 v[130:131], v[44:45]
	v_mov_b64_e32 v[82:83], v[32:33]
	s_cbranch_vccz .LBB0_841

.LBB0_833:
	s_or_saveexec_b64 s[0:1], s[0:1]
	v_mov_b32_e32 v48, 7
	s_xor_b64 exec, exec, s[0:1]
	v_mov_b32_e32 v48, 8
	v_lshl_add_u32 v68, s63, 8, v147
	s_or_b64 exec, exec, s[0:1]
	v_ashrrev_i32_e32 v69, 31, v68
	v_readlane_b32 s24, v252, 6
	s_ashr_i32 s0, s62, 3
	v_lshlrev_b64 v[66:67], 2, v[68:69]
	v_readlane_b32 s30, v252, 12
	v_readlane_b32 s31, v252, 13
	s_add_i32 s0, s0, s8
	s_and_b32 s21, s62, -8
	v_lshl_add_u64 v[70:71], s[30:31], 0, v[66:67]
	v_mad_i64_i32 v[70:71], s[6:7], s0, v231, v[70:71]
	s_add_i32 s1, s21, 0x4000
	v_readlane_b32 s25, v252, 7
	v_readlane_b32 s26, v252, 8
	v_readlane_b32 s27, v252, 9
	v_readlane_b32 s28, v252, 10
	v_readlane_b32 s29, v252, 11
	s_movk_i32 s23, 0x5000
	v_lshl_add_u32 v244, v147, 2, s23
	ds_read_b32 v151, v244
	ds_read_b32 v152, v244 offset:2048
	ds_read_b32 v153, v244 offset:4096
	ds_read_b32 v70, v244 offset:6144
	ds_read_b32 v66, v244 offset:8192
	s_waitcnt vmcnt(20)
	v_mov_b32_e32 v138, v246
	v_mov_b32_e32 v139, v247
	v_mov_b32_e32 v140, v248
	v_lshlrev_b32_e32 v141, 16, v249
	v_lshlrev_b32_e32 v148, 16, v250
	v_lshlrev_b32_e32 v149, 16, v251
	v_lshlrev_b32_e32 v69, 16, v241
	v_lshlrev_b32_e32 v68, 16, v216
	v_lshlrev_b32_e32 v150, 16, v217
	v_lshlrev_b32_e32 v72, 16, v218
	v_lshlrev_b32_e32 v73, 16, v242
	s_waitcnt lgkmcnt(0)
	v_fma_f32 v67, v138, v151, v66
	v_fmac_f32_e32 v67, v139, v152
	v_fmac_f32_e32 v67, v140, v153
	v_fmac_f32_e32 v67, v70, v141
	v_mul_f32_e32 v71, 0xbfb8aa3b, v67
	v_exp_f32_e32 v71, v71
	s_nop 0
	v_add_f32_e32 v71, 1.0, v71
	v_rcp_f32_e32 v71, v71
	s_nop 0
	v_mul_f32_e32 v67, v67, v71
	ds_write_b32 v219, v67
	v_fma_f32 v67, v139, v151, v66
	v_fmac_f32_e32 v67, v140, v152
	v_fmac_f32_e32 v67, v153, v141
	v_fmac_f32_e32 v67, v70, v148
	v_mul_f32_e32 v71, 0xbfb8aa3b, v67
	v_exp_f32_e32 v71, v71
	s_nop 0
	v_add_f32_e32 v71, 1.0, v71
	v_rcp_f32_e32 v71, v71
	s_nop 0
	v_mul_f32_e32 v67, v67, v71
	v_lshlrev_b32_e64 v71, v48, 1
	v_lshl_add_u32 v71, v71, 2, v219
	ds_write_b32 v71, v67
	v_fma_f32 v67, v140, v151, v66
	v_fmac_f32_e32 v67, v152, v141
	v_fmac_f32_e32 v67, v153, v148
	v_fmac_f32_e32 v67, v70, v149
	v_mul_f32_e32 v71, 0xbfb8aa3b, v67
	v_exp_f32_e32 v71, v71
	s_nop 0
	v_add_f32_e32 v71, 1.0, v71
	v_rcp_f32_e32 v71, v71
	s_nop 0
	v_mul_f32_e32 v67, v67, v71
	v_lshlrev_b32_e64 v71, v48, 2
	v_lshl_add_u32 v71, v71, 2, v219
	ds_write_b32 v71, v67
	v_fma_f32 v67, v151, v141, v66
	v_fmac_f32_e32 v67, v152, v148
	v_fmac_f32_e32 v67, v153, v149
	v_fmac_f32_e32 v67, v70, v69
	v_mul_f32_e32 v71, 0xbfb8aa3b, v67
	v_exp_f32_e32 v71, v71
	s_nop 0
	v_add_f32_e32 v71, 1.0, v71
	v_rcp_f32_e32 v71, v71
	s_nop 0
	v_mul_f32_e32 v67, v67, v71
	v_lshlrev_b32_e64 v71, v48, 3
	v_lshl_add_u32 v71, v71, 2, v219
	ds_write_b32 v71, v67
	v_fma_f32 v67, v151, v148, v66
	v_fmac_f32_e32 v67, v152, v149
	v_fmac_f32_e32 v67, v153, v69
	v_fmac_f32_e32 v67, v70, v68
	v_mul_f32_e32 v71, 0xbfb8aa3b, v67
	v_exp_f32_e32 v71, v71
	s_nop 0
	v_add_f32_e32 v71, 1.0, v71
	v_rcp_f32_e32 v71, v71
	s_nop 0
	v_mul_f32_e32 v67, v67, v71
	v_lshlrev_b32_e64 v71, v48, 4
	v_lshl_add_u32 v71, v71, 2, v219
	ds_write_b32 v71, v67
	v_fma_f32 v67, v151, v149, v66
	v_fmac_f32_e32 v67, v152, v69
	v_fmac_f32_e32 v67, v153, v68
	v_fmac_f32_e32 v67, v70, v150
	v_mul_f32_e32 v71, 0xbfb8aa3b, v67
	v_exp_f32_e32 v71, v71
	s_nop 0
	v_add_f32_e32 v71, 1.0, v71
	v_rcp_f32_e32 v71, v71
	s_nop 0
	v_mul_f32_e32 v67, v67, v71
	v_lshlrev_b32_e64 v71, v48, 5
	v_lshl_add_u32 v71, v71, 2, v219
	ds_write_b32 v71, v67
	v_fma_f32 v67, v151, v69, v66
	v_fmac_f32_e32 v67, v152, v68
	v_fmac_f32_e32 v67, v153, v150
	v_fmac_f32_e32 v67, v70, v72
	v_mul_f32_e32 v69, 0xbfb8aa3b, v67
	v_exp_f32_e32 v69, v69
	v_fmac_f32_e32 v66, v151, v68
	v_fmac_f32_e32 v66, v152, v150
	v_fmac_f32_e32 v66, v153, v72
	v_add_f32_e32 v69, 1.0, v69
	v_rcp_f32_e32 v69, v69
	v_fmac_f32_e32 v66, v70, v73
	v_mul_f32_e32 v67, v67, v69
	v_lshlrev_b32_e64 v69, v48, 6
	v_lshl_add_u32 v69, v69, 2, v219
	ds_write_b32 v69, v67
	v_mul_f32_e32 v67, 0xbfb8aa3b, v66
	v_exp_f32_e32 v67, v67
	v_lshlrev_b32_e64 v48, v48, 7
	v_lshl_add_u32 v48, v48, 2, v219
	v_add_f32_e32 v67, 1.0, v67
	v_rcp_f32_e32 v67, v67
	s_nop 0
	v_mul_f32_e32 v66, v66, v67
	ds_write_b32 v48, v66
	s_mov_b64 s[6:7], exec
	v_readlane_b32 s22, v255, 14
	v_readlane_b32 s23, v255, 15
	s_and_b64 s[22:23], s[6:7], s[22:23]
	s_mov_b64 exec, s[22:23]
	s_cbranch_execz .LBB0_839
	v_add_u32_e32 v66, s1, v213
	v_ashrrev_i32_e32 v67, 31, v66
	v_readlane_b32 s22, v255, 8
	v_lshl_or_b32 v68, s63, 2, v214
	v_lshlrev_b64 v[66:67], 7, v[66:67]
	v_readlane_b32 s23, v255, 9
	v_lshlrev_b32_e32 v48, 2, v68
	v_readlane_b32 s24, v252, 39
	v_lshl_add_u64 v[66:67], s[22:23], 0, v[66:67]
	v_lshl_add_u64 v[66:67], v[66:67], 0, v[48:49]
	v_or_b32_e32 v48, s11, v68
	v_readlane_b32 s28, v252, 43
	v_readlane_b32 s29, v252, 44
	v_mov_b32_e32 v69, v243
	v_readlane_b32 s25, v252, 40
	v_lshl_add_u64 v[66:67], v[48:49], 2, s[28:29]
	ds_read_b32 v66, v244 offset:10240
	v_readlane_b32 s26, v252, 41
	v_readlane_b32 s27, v252, 42
	v_readlane_b32 s30, v252, 45
	v_readlane_b32 s31, v252, 46
	s_waitcnt lgkmcnt(0)
	v_add_f32_e32 v66, v69, v66
	v_cmp_nlt_f32_e32 vcc, s19, v66
	s_and_saveexec_b64 s[40:41], vcc
	s_cbranch_execz .LBB0_838
	v_mul_f32_e32 v66, 0x3fb8aa3b, v66
	v_exp_f32_e32 v150, v66
	s_mov_b32 s1, 0x3f317218
	v_add_f32_e32 v68, 1.0, v150
	v_frexp_mant_f32_e32 v70, v68
	v_cvt_f64_f32_e32 v[66:67], v68
	v_frexp_exp_i32_f64_e32 v66, v[66:67]
	v_cmp_gt_f32_e32 vcc, s64, v70
	v_add_f32_e32 v69, -1.0, v68
	v_sub_f32_e32 v71, v69, v68
	v_subbrev_co_u32_e32 v138, vcc, 0, v66, vcc
	v_sub_u32_e32 v66, 0, v138
	v_sub_f32_e32 v69, v150, v69
	v_add_f32_e32 v71, 1.0, v71
	v_ldexp_f32 v67, v68, v66
	v_add_f32_e32 v69, v69, v71
	v_add_f32_e32 v68, -1.0, v67
	v_add_f32_e32 v70, 1.0, v67
	v_ldexp_f32 v66, v69, v66
	v_add_f32_e32 v69, 1.0, v68
	v_add_f32_e32 v71, -1.0, v70
	v_sub_f32_e32 v69, v67, v69
	v_sub_f32_e32 v67, v67, v71
	v_add_f32_e32 v69, v66, v69
	v_add_f32_e32 v66, v66, v67
	v_add_f32_e32 v139, v70, v66
	v_rcp_f32_e32 v141, v139
	v_sub_f32_e32 v67, v139, v70
	v_sub_f32_e32 v140, v66, v67
	v_add_f32_e32 v67, v68, v69
	v_mul_f32_e32 v149, v67, v141
	v_sub_f32_e32 v66, v67, v68
	v_mul_f32_e32 v68, v139, v149
	v_fma_f32 v70, v149, v139, -v68
	v_fmac_f32_e32 v70, v149, v140
	v_sub_f32_e32 v148, v69, v66
	v_add_f32_e32 v66, v68, v70
	v_sub_f32_e32 v69, v67, v66
	v_pk_add_f32 v[72:73], v[66:67], v[68:69] neg_lo:[0,1] neg_hi:[0,1]
	v_mov_b32_e32 v71, v66
	v_pk_add_f32 v[66:67], v[72:73], v[70:71] neg_lo:[0,1] neg_hi:[0,1]
	s_nop 0
	v_add_f32_e32 v67, v148, v67
	v_add_f32_e32 v66, v66, v67
	v_add_f32_e32 v67, v69, v66
	v_mul_f32_e32 v148, v141, v67
	v_mul_f32_e32 v68, v139, v148
	v_fma_f32 v70, v148, v139, -v68
	v_fmac_f32_e32 v70, v148, v140
	v_sub_f32_e32 v69, v69, v67
	v_add_f32_e32 v139, v66, v69
	v_add_f32_e32 v66, v68, v70
	v_sub_f32_e32 v69, v67, v66
	v_pk_add_f32 v[72:73], v[66:67], v[68:69] neg_lo:[0,1] neg_hi:[0,1]
	v_mov_b32_e32 v71, v66
	v_pk_add_f32 v[66:67], v[72:73], v[70:71] neg_lo:[0,1] neg_hi:[0,1]
	s_nop 0
	v_add_f32_e32 v67, v139, v67
	v_add_f32_e32 v66, v66, v67
	v_add_f32_e32 v67, v149, v148
	v_add_f32_e32 v66, v69, v66
	v_sub_f32_e32 v68, v67, v149
	v_mul_f32_e32 v66, v141, v66
	v_sub_f32_e32 v68, v148, v68
	v_add_f32_e32 v68, v68, v66
	v_add_f32_e32 v70, v67, v68
	v_mul_f32_e32 v71, v70, v70
	v_fmamk_f32 v66, v71, 0x3e9b6dac, v236
	v_fmaak_f32 v207, v71, v66, 0x3f2aaada
	v_cvt_f32_i32_e32 v66, v138
	v_sub_f32_e32 v67, v70, v67
	v_sub_f32_e32 v67, v68, v67
	v_ldexp_f32 v72, v67, 1
	v_mul_f32_e32 v67, v70, v71
	v_ldexp_f32 v69, v70, 1
	v_pk_mul_f32 v[70:71], v[66:67], v[206:207]
	s_nop 0
	v_fma_f32 v68, v66, s1, -v70
	v_fmac_f32_e32 v68, 0xb102e308, v66
	v_pk_add_f32 v[66:67], v[70:71], v[68:69]
	s_mov_b32 s1, 0x7f800000
	v_sub_f32_e32 v69, v67, v69
	v_sub_f32_e32 v69, v71, v69
	v_add_f32_e32 v73, v72, v69
	v_mov_b32_e32 v72, v70
	v_pk_add_f32 v[70:71], v[66:67], v[70:71] neg_lo:[0,1] neg_hi:[0,1]
	v_pk_add_f32 v[138:139], v[66:67], v[72:73]
	v_mov_b32_e32 v69, v66
	v_mov_b32_e32 v71, v139
	v_pk_add_f32 v[140:141], v[68:69], v[70:71] neg_lo:[0,1] neg_hi:[0,1]
	v_pk_add_f32 v[68:69], v[68:69], v[70:71]
	v_mov_b32_e32 v72, v73
	v_pk_add_f32 v[70:71], v[68:69], v[66:67] op_sel:[1,0] op_sel_hi:[0,1] neg_lo:[0,1] neg_hi:[0,1]
	v_pk_add_f32 v[148:149], v[138:139], v[70:71] op_sel_hi:[1,0] neg_lo:[0,1] neg_hi:[0,1]
	v_mov_b32_e32 v138, v139
	v_mov_b32_e32 v139, v69
	v_pk_mov_b32 v[70:71], v[66:67], v[70:71] op_sel:[1,0]
	v_mov_b32_e32 v73, v66
	v_pk_add_f32 v[70:71], v[138:139], v[70:71] neg_lo:[0,1] neg_hi:[0,1]
	v_mov_b32_e32 v148, v140
	v_pk_add_f32 v[66:67], v[72:73], v[70:71] neg_lo:[0,1] neg_hi:[0,1]
	v_mov_b32_e32 v141, v69
	v_pk_add_f32 v[70:71], v[148:149], v[66:67]
	v_cmp_neq_f32_e32 vcc, s1, v150
	v_pk_add_f32 v[72:73], v[70:71], v[70:71] op_sel:[0,1] op_sel_hi:[1,0]
	s_mov_b32 s1, 0x33800000
	v_pk_add_f32 v[68:69], v[68:69], v[72:73] op_sel:[1,0] op_sel_hi:[0,1]
	v_mov_b32_e32 v71, v68
	v_pk_add_f32 v[138:139], v[70:71], v[140:141] neg_lo:[0,1] neg_hi:[0,1]
	v_mov_b32_e32 v67, v72
	v_sub_f32_e32 v69, v70, v138
	v_pk_add_f32 v[66:67], v[66:67], v[138:139] neg_lo:[0,1] neg_hi:[0,1]
	v_sub_f32_e32 v69, v140, v69
	v_add_f32_e32 v66, v66, v69
	v_add_f32_e32 v66, v66, v67
	v_add_f32_e32 v66, v68, v66
	v_cndmask_b32_e32 v66, v237, v66, vcc
	v_cmp_ngt_f32_e32 vcc, -1.0, v150
	s_nop 1
	v_cndmask_b32_e32 v66, v238, v66, vcc
	v_cmp_neq_f32_e32 vcc, -1.0, v150
	s_nop 1
	v_cndmask_b32_e32 v66, v239, v66, vcc
	v_cmp_lt_f32_e64 vcc, |v150|, s1
	s_nop 1
	v_cndmask_b32_e32 v66, v66, v150, vcc
.LBB0_838:
	s_or_b64 exec, exec, s[40:41]
	v_readlane_b32 s24, v252, 39
	v_readlane_b32 s30, v252, 45
	v_readlane_b32 s31, v252, 46
	v_add_u32_e32 v67, 0x4000, v212
	v_readlane_b32 s25, v252, 40
	v_lshl_add_u64 v[68:69], v[48:49], 2, s[30:31]
	ds_read_b32 v48, v244 offset:12288
	v_readlane_b32 s26, v252, 41
	v_readlane_b32 s27, v252, 42
	v_readlane_b32 s28, v252, 43
	v_readlane_b32 s29, v252, 44
	s_waitcnt lgkmcnt(0)
	v_mul_f32_e32 v48, 0x3fb8aa3b, v48
	v_exp_f32_e32 v48, v48
	s_nop 0
	v_mul_f32_e64 v48, v48, -v66
	v_mul_f32_e32 v48, 0x3fb8aa3b, v48
	v_exp_f32_e32 v48, v48
	ds_write2_b32 v67, v66, v48 offset1:32
